# LDS-DMA issue: address add moved between the M0 write and the DMA instruction as the required wait state; 78 s_nop fillers removed (GEMM loops, peeled copies, attention tile loads)
# baseline (speedup 1.0000x reference)
.LBB0_490:
	v_mov_b64_e32 v[2:3], s[26:27]
	s_ashr_i32 s41, s40, 31
	v_cmp_lt_i64_e32 vcc, s[16:17], v[2:3]
	s_lshl_b64 s[16:17], s[40:41], 19
	s_add_u32 s44, s46, s16
	s_addc_u32 s45, s47, s17
	s_and_b64 s[16:17], vcc, exec
	s_cselect_b32 s9, s45, s13
	s_cselect_b32 s11, s44, s12
	s_ashr_i32 s39, s38, 31
	s_lshl_b64 s[16:17], s[38:39], 19
	s_add_u32 s54, s71, s16
	s_addc_u32 s55, s73, s17
	s_and_b64 s[16:17], vcc, exec
	s_cselect_b32 s39, s55, s15
	s_cselect_b32 s41, s54, s14
	s_add_u32 s12, s12, 0x40080
	s_addc_u32 s13, s13, 0
	s_add_u32 s62, s14, 0x100
	s_addc_u32 s63, s15, 0
	s_mov_b32 s64, -2
	s_add_u32 s14, s12, 0xfffc0080
	s_addc_u32 s15, s13, -1
	s_add_i32 s65, 0, 0x10000
	v_add_u32_e32 v0, s65, v230
	ds_read_b128 v[2:5], v0
	ds_read_b128 v[6:9], v0 offset:1024
	ds_read_b128 v[10:13], v0 offset:2048
	ds_read_b128 v[14:17], v0 offset:3072
	s_cmp_eq_u32 s64, 12
	s_cselect_b32 s17, s9, s15
	s_cselect_b32 s16, s11, s14
	s_cselect_b32 s15, s39, s63
	s_cselect_b32 s14, s41, s62
	v_lshl_add_u64 v[50:51], s[12:13], 0, v[214:215]
	s_add_i32 m0, s23, 0xc000
	ds_read_b128 v[18:21], v232
	ds_read_b128 v[22:25], v232 offset:1024
	ds_read_b128 v[26:29], v232 offset:2048
	ds_read_b128 v[30:33], v232 offset:3072
	ds_read_b128 v[34:37], v232 offset:4096
	ds_read_b128 v[38:41], v232 offset:5120
	ds_read_b128 v[42:45], v232 offset:6144
	ds_read_b128 v[46:49], v232 offset:7168
	global_load_lds_dwordx4 v[50:51], off
	s_add_i32 m0, s23, 0xe000
	v_lshl_add_u64 v[50:51], s[12:13], 0, v[216:217]
	global_load_lds_dwordx4 v[50:51], off
	s_waitcnt lgkmcnt(8)
	s_barrier
	s_waitcnt lgkmcnt(0)
	v_mfma_f32_16x16x32_bf16 v[158:161], v[2:5], v[34:37], 0
	v_mfma_f32_16x16x32_bf16 v[154:157], v[10:13], v[34:37], 0
	v_mfma_f32_16x16x32_bf16 v[138:141], v[2:5], v[42:45], 0
	v_mfma_f32_16x16x32_bf16 v[134:137], v[10:13], v[42:45], 0
	v_mfma_f32_16x16x32_bf16 v[50:53], v[2:5], v[18:21], 0
	v_mfma_f32_16x16x32_bf16 v[54:57], v[10:13], v[18:21], 0
	v_mfma_f32_16x16x32_bf16 v[58:61], v[2:5], v[26:29], 0
	v_mfma_f32_16x16x32_bf16 v[150:153], v[10:13], v[26:29], 0
	v_mfma_f32_16x16x32_bf16 v[158:161], v[6:9], v[38:41], v[158:161]
	v_mfma_f32_16x16x32_bf16 v[154:157], v[14:17], v[38:41], v[154:157]
	v_mfma_f32_16x16x32_bf16 v[138:141], v[6:9], v[46:49], v[138:141]
	v_mfma_f32_16x16x32_bf16 v[134:137], v[14:17], v[46:49], v[134:137]
	v_mfma_f32_16x16x32_bf16 v[50:53], v[6:9], v[22:25], v[50:53]
	v_mfma_f32_16x16x32_bf16 v[54:57], v[14:17], v[22:25], v[54:57]
	v_mfma_f32_16x16x32_bf16 v[58:61], v[6:9], v[30:33], v[58:61]
	v_mfma_f32_16x16x32_bf16 v[150:153], v[14:17], v[30:33], v[150:153]
	s_barrier
	s_add_i32 s86, 0, 0x14000
	s_add_i32 s65, s65, s22
	v_add_u32_e32 v0, s86, v230
	v_lshl_add_u64 v[222:223], s[14:15], 0, v[208:209]
	s_mov_b32 m0, s65
	ds_read_b128 v[162:165], v0
	ds_read_b128 v[174:177], v0 offset:1024
	ds_read_b128 v[178:181], v0 offset:2048
	ds_read_b128 v[182:185], v0 offset:3072
	global_load_lds_dwordx4 v[222:223], off
	s_add_i32 m0, s65, 0x2000
	v_lshl_add_u64 v[226:227], s[14:15], 0, v[212:213]
	global_load_lds_dwordx4 v[226:227], off
	s_barrier
	s_waitcnt lgkmcnt(0)
	v_mfma_f32_16x16x32_bf16 v[186:189], v[162:165], v[18:21], 0
	v_mfma_f32_16x16x32_bf16 v[18:21], v[178:181], v[18:21], 0
	v_mfma_f32_16x16x32_bf16 v[186:189], v[174:177], v[22:25], v[186:189]
	v_mfma_f32_16x16x32_bf16 v[18:21], v[182:185], v[22:25], v[18:21]
	v_mfma_f32_16x16x32_bf16 v[22:25], v[162:165], v[26:29], 0
	v_mfma_f32_16x16x32_bf16 v[26:29], v[178:181], v[26:29], 0
	v_mfma_f32_16x16x32_bf16 v[22:25], v[174:177], v[30:33], v[22:25]
	v_mfma_f32_16x16x32_bf16 v[26:29], v[182:185], v[30:33], v[26:29]
	v_mfma_f32_16x16x32_bf16 v[30:33], v[162:165], v[34:37], 0
	v_mfma_f32_16x16x32_bf16 v[34:37], v[178:181], v[34:37], 0
	v_mfma_f32_16x16x32_bf16 v[30:33], v[174:177], v[38:41], v[30:33]
	v_mfma_f32_16x16x32_bf16 v[34:37], v[182:185], v[38:41], v[34:37]
	v_mfma_f32_16x16x32_bf16 v[38:41], v[162:165], v[42:45], 0
	v_mfma_f32_16x16x32_bf16 v[42:45], v[178:181], v[42:45], 0
	v_mfma_f32_16x16x32_bf16 v[38:41], v[174:177], v[46:49], v[38:41]
	v_mfma_f32_16x16x32_bf16 v[42:45], v[182:185], v[46:49], v[42:45]
	s_mov_b32 m0, s23
	v_lshl_add_u64 v[238:239], s[16:17], 0, v[206:207]
	s_barrier
	ds_read_b128 v[46:49], v232 offset:16384
	ds_read_b128 v[126:129], v232 offset:17408
	ds_read_b128 v[130:133], v232 offset:18432
	ds_read_b128 v[142:145], v232 offset:19456
	ds_read_b128 v[146:149], v232 offset:20480
	ds_read_b128 v[166:169], v232 offset:21504
	ds_read_b128 v[170:173], v232 offset:22528
	ds_read_b128 v[190:193], v232 offset:23552
	global_load_lds_dwordx4 v[238:239], off
	s_mov_b32 m0, s72
	v_lshl_add_u64 v[240:241], s[16:17], 0, v[210:211]
	global_load_lds_dwordx4 v[240:241], off
	s_barrier
	s_waitcnt lgkmcnt(0)
	v_mfma_f32_16x16x32_bf16 v[122:125], v[2:5], v[46:49], 0
	v_mfma_f32_16x16x32_bf16 v[118:121], v[10:13], v[46:49], 0
	v_mfma_f32_16x16x32_bf16 v[106:109], v[2:5], v[130:133], 0
	v_mfma_f32_16x16x32_bf16 v[102:105], v[10:13], v[130:133], 0
	v_mfma_f32_16x16x32_bf16 v[90:93], v[2:5], v[146:149], 0
	v_mfma_f32_16x16x32_bf16 v[86:89], v[10:13], v[146:149], 0
	v_mfma_f32_16x16x32_bf16 v[2:5], v[2:5], v[170:173], 0
	v_mfma_f32_16x16x32_bf16 v[122:125], v[6:9], v[126:129], v[122:125]
	v_mfma_f32_16x16x32_bf16 v[118:121], v[14:17], v[126:129], v[118:121]
	v_mfma_f32_16x16x32_bf16 v[106:109], v[6:9], v[142:145], v[106:109]
	v_mfma_f32_16x16x32_bf16 v[102:105], v[14:17], v[142:145], v[102:105]
	v_mfma_f32_16x16x32_bf16 v[90:93], v[6:9], v[166:169], v[90:93]
	v_mfma_f32_16x16x32_bf16 v[86:89], v[14:17], v[166:169], v[86:89]
	v_mfma_f32_16x16x32_bf16 v[2:5], v[6:9], v[190:193], v[2:5]
	v_mfma_f32_16x16x32_bf16 v[6:9], v[10:13], v[170:173], 0
	v_mfma_f32_16x16x32_bf16 v[6:9], v[14:17], v[190:193], v[6:9]
	s_barrier
	s_add_u32 s66, s14, 0x40000
	s_addc_u32 s67, s15, 0
	s_add_i32 s65, s86, s22
	s_mov_b32 m0, s65
	v_lshl_add_u64 v[10:11], s[66:67], 0, v[208:209]
	global_load_lds_dwordx4 v[10:11], off
	s_add_i32 m0, s65, 0x2000
	v_lshl_add_u64 v[10:11], s[66:67], 0, v[212:213]
	global_load_lds_dwordx4 v[10:11], off
	s_waitcnt vmcnt(6)
	s_barrier
	v_mfma_f32_16x16x32_bf16 v[70:73], v[178:181], v[130:133], 0
	v_mfma_f32_16x16x32_bf16 v[94:97], v[182:185], v[142:145], v[70:73]
	v_mfma_f32_16x16x32_bf16 v[70:73], v[162:165], v[146:149], 0
	v_mfma_f32_16x16x32_bf16 v[82:85], v[174:177], v[166:169], v[70:73]
	v_mfma_f32_16x16x32_bf16 v[70:73], v[178:181], v[146:149], 0
	v_mfma_f32_16x16x32_bf16 v[66:69], v[162:165], v[170:173], 0
	v_mfma_f32_16x16x32_bf16 v[62:65], v[178:181], v[170:173], 0
	v_mfma_f32_16x16x32_bf16 v[10:13], v[162:165], v[46:49], 0
	v_mfma_f32_16x16x32_bf16 v[14:17], v[178:181], v[46:49], 0
	v_mfma_f32_16x16x32_bf16 v[46:49], v[162:165], v[130:133], 0
	v_mfma_f32_16x16x32_bf16 v[78:81], v[182:185], v[166:169], v[70:73]
	v_mfma_f32_16x16x32_bf16 v[66:69], v[174:177], v[190:193], v[66:69]
	v_mfma_f32_16x16x32_bf16 v[62:65], v[182:185], v[190:193], v[62:65]
	v_mfma_f32_16x16x32_bf16 v[10:13], v[174:177], v[126:129], v[10:13]
	v_mfma_f32_16x16x32_bf16 v[14:17], v[182:185], v[126:129], v[14:17]
	v_mfma_f32_16x16x32_bf16 v[46:49], v[174:177], v[142:145], v[46:49]
	s_add_i32 s65, 0, 0x18000
	v_add_u32_e32 v0, s65, v230
	s_barrier
	ds_read_b128 v[70:73], v0
	ds_read_b128 v[74:77], v0 offset:1024
	ds_read_b128 v[98:101], v0 offset:2048
	ds_read_b128 v[110:113], v0 offset:3072
	s_add_u32 s16, s16, 0x40000
	s_addc_u32 s17, s17, 0
	s_mov_b32 m0, s83
	v_lshl_add_u64 v[146:147], s[16:17], 0, v[206:207]
	ds_read_b128 v[114:117], v232 offset:32768
	ds_read_b128 v[126:129], v232 offset:33792
	ds_read_b128 v[130:133], v232 offset:34816
	ds_read_b128 v[142:145], v232 offset:35840
	ds_read_b128 v[162:165], v232 offset:36864
	ds_read_b128 v[174:177], v232 offset:37888
	ds_read_b128 v[218:221], v232 offset:38912
	ds_read_b128 v[234:237], v232 offset:39936
	global_load_lds_dwordx4 v[146:147], off
	s_mov_b32 m0, s84
	v_lshl_add_u64 v[146:147], s[16:17], 0, v[210:211]
	global_load_lds_dwordx4 v[146:147], off
	s_waitcnt lgkmcnt(8)
	s_barrier
	s_waitcnt lgkmcnt(0)
	v_mfma_f32_16x16x32_bf16 v[50:53], v[70:73], v[114:117], v[50:53]
	v_mfma_f32_16x16x32_bf16 v[202:205], v[74:77], v[126:129], v[50:53]
	v_mfma_f32_16x16x32_bf16 v[50:53], v[98:101], v[114:117], v[54:57]
	v_mfma_f32_16x16x32_bf16 v[198:201], v[110:113], v[126:129], v[50:53]
	v_mfma_f32_16x16x32_bf16 v[50:53], v[70:73], v[130:133], v[58:61]
	v_mfma_f32_16x16x32_bf16 v[182:185], v[74:77], v[142:145], v[50:53]
	v_mfma_f32_16x16x32_bf16 v[50:53], v[98:101], v[130:133], v[150:153]
	v_mfma_f32_16x16x32_bf16 v[178:181], v[110:113], v[142:145], v[50:53]
	v_mfma_f32_16x16x32_bf16 v[50:53], v[70:73], v[162:165], v[158:161]
	v_mfma_f32_16x16x32_bf16 v[158:161], v[74:77], v[174:177], v[50:53]
	v_mfma_f32_16x16x32_bf16 v[50:53], v[98:101], v[162:165], v[154:157]
	v_mfma_f32_16x16x32_bf16 v[154:157], v[110:113], v[174:177], v[50:53]
	v_mfma_f32_16x16x32_bf16 v[50:53], v[70:73], v[218:221], v[138:141]
	v_mfma_f32_16x16x32_bf16 v[138:141], v[74:77], v[234:237], v[50:53]
	v_mfma_f32_16x16x32_bf16 v[50:53], v[98:101], v[218:221], v[134:137]
	v_mfma_f32_16x16x32_bf16 v[134:137], v[110:113], v[234:237], v[50:53]
	s_barrier
	s_add_i32 s16, 0, 0x1c000
	s_add_i32 s17, s65, s22
	v_add_u32_e32 v0, s16, v230
	v_lshl_add_u64 v[146:147], v[222:223], 0, s[20:21]
	s_mov_b32 m0, s17
	ds_read_b128 v[50:53], v0
	ds_read_b128 v[54:57], v0 offset:1024
	ds_read_b128 v[58:61], v0 offset:2048
	ds_read_b128 v[150:153], v0 offset:3072
	global_load_lds_dwordx4 v[146:147], off
	s_add_i32 m0, s17, 0x2000
	v_lshl_add_u64 v[146:147], v[226:227], 0, s[20:21]
	global_load_lds_dwordx4 v[146:147], off
	s_barrier
	s_waitcnt lgkmcnt(0)
	v_mfma_f32_16x16x32_bf16 v[18:21], v[58:61], v[114:117], v[18:21]
	v_mfma_f32_16x16x32_bf16 v[190:193], v[150:153], v[126:129], v[18:21]
	v_mfma_f32_16x16x32_bf16 v[18:21], v[50:53], v[130:133], v[22:25]
	v_mfma_f32_16x16x32_bf16 v[170:173], v[54:57], v[142:145], v[18:21]
	v_mfma_f32_16x16x32_bf16 v[18:21], v[58:61], v[130:133], v[26:29]
	v_mfma_f32_16x16x32_bf16 v[146:149], v[50:53], v[114:117], v[186:189]
	v_mfma_f32_16x16x32_bf16 v[166:169], v[150:153], v[142:145], v[18:21]
	v_mfma_f32_16x16x32_bf16 v[18:21], v[50:53], v[162:165], v[30:33]
	v_mfma_f32_16x16x32_bf16 v[194:197], v[54:57], v[126:129], v[146:149]
	v_mfma_f32_16x16x32_bf16 v[146:149], v[54:57], v[174:177], v[18:21]
	v_mfma_f32_16x16x32_bf16 v[18:21], v[58:61], v[162:165], v[34:37]
	v_mfma_f32_16x16x32_bf16 v[142:145], v[150:153], v[174:177], v[18:21]
	v_mfma_f32_16x16x32_bf16 v[18:21], v[50:53], v[218:221], v[38:41]
	v_mfma_f32_16x16x32_bf16 v[130:133], v[54:57], v[234:237], v[18:21]
	v_mfma_f32_16x16x32_bf16 v[18:21], v[58:61], v[218:221], v[42:45]
	v_mfma_f32_16x16x32_bf16 v[126:129], v[150:153], v[234:237], v[18:21]
	s_mov_b32 m0, s91
	v_lshl_add_u64 v[114:115], v[238:239], 0, s[20:21]
	s_barrier
	s_nop 2
	ds_read_b128 v[18:21], v232 offset:49152
	ds_read_b128 v[22:25], v232 offset:50176
	ds_read_b128 v[26:29], v232 offset:51200
	ds_read_b128 v[30:33], v232 offset:52224
	ds_read_b128 v[34:37], v232 offset:53248
	ds_read_b128 v[38:41], v232 offset:54272
	ds_read_b128 v[42:45], v232 offset:55296
	ds_read_b128 v[162:165], v232 offset:56320
	global_load_lds_dwordx4 v[114:115], off
	s_mov_b32 m0, s59
	v_lshl_add_u64 v[114:115], v[240:241], 0, s[20:21]
	global_load_lds_dwordx4 v[114:115], off
	s_barrier
	s_waitcnt lgkmcnt(0)
	v_mfma_f32_16x16x32_bf16 v[114:117], v[70:73], v[18:21], v[122:125]
	v_mfma_f32_16x16x32_bf16 v[106:109], v[70:73], v[26:29], v[106:109]
	v_mfma_f32_16x16x32_bf16 v[90:93], v[70:73], v[34:37], v[90:93]
	v_mfma_f32_16x16x32_bf16 v[2:5], v[70:73], v[42:45], v[2:5]
	v_mfma_f32_16x16x32_bf16 v[122:125], v[74:77], v[22:25], v[114:117]
	v_mfma_f32_16x16x32_bf16 v[114:117], v[98:101], v[18:21], v[118:121]
	v_mfma_f32_16x16x32_bf16 v[106:109], v[74:77], v[30:33], v[106:109]
	v_mfma_f32_16x16x32_bf16 v[102:105], v[98:101], v[26:29], v[102:105]
	v_mfma_f32_16x16x32_bf16 v[90:93], v[74:77], v[38:41], v[90:93]
	v_mfma_f32_16x16x32_bf16 v[86:89], v[98:101], v[34:37], v[86:89]
	v_mfma_f32_16x16x32_bf16 v[74:77], v[74:77], v[162:165], v[2:5]
	v_mfma_f32_16x16x32_bf16 v[2:5], v[98:101], v[42:45], v[6:9]
	v_mfma_f32_16x16x32_bf16 v[118:121], v[110:113], v[22:25], v[114:117]
	v_mfma_f32_16x16x32_bf16 v[102:105], v[110:113], v[30:33], v[102:105]
	v_mfma_f32_16x16x32_bf16 v[86:89], v[110:113], v[38:41], v[86:89]
	v_mfma_f32_16x16x32_bf16 v[70:73], v[110:113], v[162:165], v[2:5]
	s_barrier
	s_add_u32 s14, s14, 0x40080
	s_addc_u32 s15, s15, 0
	s_add_i32 s16, s16, s22
	s_mov_b32 m0, s16
	v_lshl_add_u64 v[2:3], s[14:15], 0, v[208:209]
	global_load_lds_dwordx4 v[2:3], off
	s_add_i32 m0, s16, 0x2000
	v_lshl_add_u64 v[2:3], s[14:15], 0, v[212:213]
	global_load_lds_dwordx4 v[2:3], off
	s_waitcnt vmcnt(6)
	s_barrier
	v_mfma_f32_16x16x32_bf16 v[2:5], v[50:53], v[18:21], v[10:13]
	v_mfma_f32_16x16x32_bf16 v[114:117], v[54:57], v[22:25], v[2:5]
	v_mfma_f32_16x16x32_bf16 v[2:5], v[58:61], v[18:21], v[14:17]
	v_mfma_f32_16x16x32_bf16 v[110:113], v[150:153], v[22:25], v[2:5]
	v_mfma_f32_16x16x32_bf16 v[2:5], v[50:53], v[26:29], v[46:49]
	v_mfma_f32_16x16x32_bf16 v[98:101], v[54:57], v[30:33], v[2:5]
	v_mfma_f32_16x16x32_bf16 v[2:5], v[58:61], v[26:29], v[94:97]
	v_mfma_f32_16x16x32_bf16 v[94:97], v[150:153], v[30:33], v[2:5]
	v_mfma_f32_16x16x32_bf16 v[2:5], v[50:53], v[34:37], v[82:85]
	v_mfma_f32_16x16x32_bf16 v[82:85], v[54:57], v[38:41], v[2:5]
	v_mfma_f32_16x16x32_bf16 v[2:5], v[58:61], v[34:37], v[78:81]
	v_mfma_f32_16x16x32_bf16 v[78:81], v[150:153], v[38:41], v[2:5]
	v_mfma_f32_16x16x32_bf16 v[2:5], v[50:53], v[42:45], v[66:69]
	v_mfma_f32_16x16x32_bf16 v[66:69], v[54:57], v[162:165], v[2:5]
	v_mfma_f32_16x16x32_bf16 v[2:5], v[58:61], v[42:45], v[62:65]
	v_mfma_f32_16x16x32_bf16 v[62:65], v[150:153], v[162:165], v[2:5]
	s_add_i32 s64, s64, 2
	s_add_u32 s12, s12, 0x100
	s_addc_u32 s13, s13, 0
	s_add_u32 s62, s62, 0x100
	s_addc_u32 s63, s63, 0
	s_cmp_gt_u32 s64, 13
	s_barrier
	s_cbranch_scc0 .LBB0_491
	s_branch .Lpeel_exit_g1
.LBB0_491:
	s_add_u32 s14, s12, 0xfffc0080
	s_addc_u32 s15, s13, -1
	s_add_i32 s65, 0, 0x10000
	v_add_u32_e32 v0, s65, v230
	ds_read_b128 v[2:5], v0
	ds_read_b128 v[6:9], v0 offset:1024
	ds_read_b128 v[10:13], v0 offset:2048
	ds_read_b128 v[14:17], v0 offset:3072
	s_cmp_eq_u32 s64, 12
	s_cselect_b32 s17, s9, s15
	s_cselect_b32 s16, s11, s14
	s_cselect_b32 s15, s39, s63
	s_cselect_b32 s14, s41, s62
	v_lshl_add_u64 v[50:51], s[12:13], 0, v[214:215]
	s_add_i32 m0, s23, 0xc000
	ds_read_b128 v[18:21], v232
	ds_read_b128 v[22:25], v232 offset:1024
	ds_read_b128 v[26:29], v232 offset:2048
	ds_read_b128 v[30:33], v232 offset:3072
	ds_read_b128 v[34:37], v232 offset:4096
	ds_read_b128 v[38:41], v232 offset:5120
	ds_read_b128 v[42:45], v232 offset:6144
	ds_read_b128 v[46:49], v232 offset:7168
	global_load_lds_dwordx4 v[50:51], off
	s_add_i32 m0, s23, 0xe000
	v_lshl_add_u64 v[50:51], s[12:13], 0, v[216:217]
	global_load_lds_dwordx4 v[50:51], off
	s_waitcnt lgkmcnt(8)
	s_barrier
	s_waitcnt lgkmcnt(0)
	v_mfma_f32_16x16x32_bf16 v[158:161], v[2:5], v[34:37], v[158:161]
	v_mfma_f32_16x16x32_bf16 v[154:157], v[10:13], v[34:37], v[154:157]
	v_mfma_f32_16x16x32_bf16 v[138:141], v[2:5], v[42:45], v[138:141]
	v_mfma_f32_16x16x32_bf16 v[134:137], v[10:13], v[42:45], v[134:137]
	v_mfma_f32_16x16x32_bf16 v[50:53], v[2:5], v[18:21], v[202:205]
	v_mfma_f32_16x16x32_bf16 v[54:57], v[10:13], v[18:21], v[198:201]
	v_mfma_f32_16x16x32_bf16 v[58:61], v[2:5], v[26:29], v[182:185]
	v_mfma_f32_16x16x32_bf16 v[150:153], v[10:13], v[26:29], v[178:181]
	v_mfma_f32_16x16x32_bf16 v[158:161], v[6:9], v[38:41], v[158:161]
	v_mfma_f32_16x16x32_bf16 v[154:157], v[14:17], v[38:41], v[154:157]
	v_mfma_f32_16x16x32_bf16 v[138:141], v[6:9], v[46:49], v[138:141]
	v_mfma_f32_16x16x32_bf16 v[134:137], v[14:17], v[46:49], v[134:137]
	v_mfma_f32_16x16x32_bf16 v[50:53], v[6:9], v[22:25], v[50:53]
	v_mfma_f32_16x16x32_bf16 v[54:57], v[14:17], v[22:25], v[54:57]
	v_mfma_f32_16x16x32_bf16 v[58:61], v[6:9], v[30:33], v[58:61]
	v_mfma_f32_16x16x32_bf16 v[150:153], v[14:17], v[30:33], v[150:153]
	s_barrier
	s_add_i32 s86, 0, 0x14000
	s_add_i32 s65, s65, s22
	v_add_u32_e32 v0, s86, v230
	v_lshl_add_u64 v[222:223], s[14:15], 0, v[208:209]
	s_mov_b32 m0, s65
	ds_read_b128 v[162:165], v0
	ds_read_b128 v[174:177], v0 offset:1024
	ds_read_b128 v[178:181], v0 offset:2048
	ds_read_b128 v[182:185], v0 offset:3072
	global_load_lds_dwordx4 v[222:223], off
	s_add_i32 m0, s65, 0x2000
	v_lshl_add_u64 v[226:227], s[14:15], 0, v[212:213]
	global_load_lds_dwordx4 v[226:227], off
	s_barrier
	s_waitcnt lgkmcnt(0)
	v_mfma_f32_16x16x32_bf16 v[186:189], v[162:165], v[18:21], v[194:197]
	v_mfma_f32_16x16x32_bf16 v[18:21], v[178:181], v[18:21], v[190:193]
	v_mfma_f32_16x16x32_bf16 v[186:189], v[174:177], v[22:25], v[186:189]
	v_mfma_f32_16x16x32_bf16 v[18:21], v[182:185], v[22:25], v[18:21]
	v_mfma_f32_16x16x32_bf16 v[22:25], v[162:165], v[26:29], v[170:173]
	v_mfma_f32_16x16x32_bf16 v[26:29], v[178:181], v[26:29], v[166:169]
	v_mfma_f32_16x16x32_bf16 v[22:25], v[174:177], v[30:33], v[22:25]
	v_mfma_f32_16x16x32_bf16 v[26:29], v[182:185], v[30:33], v[26:29]
	v_mfma_f32_16x16x32_bf16 v[30:33], v[162:165], v[34:37], v[146:149]
	v_mfma_f32_16x16x32_bf16 v[34:37], v[178:181], v[34:37], v[142:145]
	v_mfma_f32_16x16x32_bf16 v[30:33], v[174:177], v[38:41], v[30:33]
	v_mfma_f32_16x16x32_bf16 v[34:37], v[182:185], v[38:41], v[34:37]
	v_mfma_f32_16x16x32_bf16 v[38:41], v[162:165], v[42:45], v[130:133]
	v_mfma_f32_16x16x32_bf16 v[42:45], v[178:181], v[42:45], v[126:129]
	v_mfma_f32_16x16x32_bf16 v[38:41], v[174:177], v[46:49], v[38:41]
	v_mfma_f32_16x16x32_bf16 v[42:45], v[182:185], v[46:49], v[42:45]
	s_mov_b32 m0, s23
	v_lshl_add_u64 v[238:239], s[16:17], 0, v[206:207]
	s_barrier
	ds_read_b128 v[46:49], v232 offset:16384
	ds_read_b128 v[126:129], v232 offset:17408
	ds_read_b128 v[130:133], v232 offset:18432
	ds_read_b128 v[142:145], v232 offset:19456
	ds_read_b128 v[146:149], v232 offset:20480
	ds_read_b128 v[166:169], v232 offset:21504
	ds_read_b128 v[170:173], v232 offset:22528
	ds_read_b128 v[190:193], v232 offset:23552
	global_load_lds_dwordx4 v[238:239], off
	s_mov_b32 m0, s72
	v_lshl_add_u64 v[240:241], s[16:17], 0, v[210:211]
	global_load_lds_dwordx4 v[240:241], off
	s_barrier
	s_waitcnt lgkmcnt(0)
	v_mfma_f32_16x16x32_bf16 v[122:125], v[2:5], v[46:49], v[122:125]
	v_mfma_f32_16x16x32_bf16 v[118:121], v[10:13], v[46:49], v[118:121]
	v_mfma_f32_16x16x32_bf16 v[106:109], v[2:5], v[130:133], v[106:109]
	v_mfma_f32_16x16x32_bf16 v[102:105], v[10:13], v[130:133], v[102:105]
	v_mfma_f32_16x16x32_bf16 v[90:93], v[2:5], v[146:149], v[90:93]
	v_mfma_f32_16x16x32_bf16 v[86:89], v[10:13], v[146:149], v[86:89]
	v_mfma_f32_16x16x32_bf16 v[2:5], v[2:5], v[170:173], v[74:77]
	v_mfma_f32_16x16x32_bf16 v[122:125], v[6:9], v[126:129], v[122:125]
	v_mfma_f32_16x16x32_bf16 v[118:121], v[14:17], v[126:129], v[118:121]
	v_mfma_f32_16x16x32_bf16 v[106:109], v[6:9], v[142:145], v[106:109]
	v_mfma_f32_16x16x32_bf16 v[102:105], v[14:17], v[142:145], v[102:105]
	v_mfma_f32_16x16x32_bf16 v[90:93], v[6:9], v[166:169], v[90:93]
	v_mfma_f32_16x16x32_bf16 v[86:89], v[14:17], v[166:169], v[86:89]
	v_mfma_f32_16x16x32_bf16 v[2:5], v[6:9], v[190:193], v[2:5]
	v_mfma_f32_16x16x32_bf16 v[6:9], v[10:13], v[170:173], v[70:73]
	v_mfma_f32_16x16x32_bf16 v[6:9], v[14:17], v[190:193], v[6:9]
	s_barrier
	s_add_u32 s66, s14, 0x40000
	s_addc_u32 s67, s15, 0
	s_add_i32 s65, s86, s22
	s_mov_b32 m0, s65
	v_lshl_add_u64 v[10:11], s[66:67], 0, v[208:209]
	global_load_lds_dwordx4 v[10:11], off
	s_add_i32 m0, s65, 0x2000
	v_lshl_add_u64 v[10:11], s[66:67], 0, v[212:213]
	global_load_lds_dwordx4 v[10:11], off
	s_waitcnt vmcnt(6)
	s_barrier
	v_mfma_f32_16x16x32_bf16 v[70:73], v[178:181], v[130:133], v[94:97]
	v_mfma_f32_16x16x32_bf16 v[94:97], v[182:185], v[142:145], v[70:73]
	v_mfma_f32_16x16x32_bf16 v[70:73], v[162:165], v[146:149], v[82:85]
	v_mfma_f32_16x16x32_bf16 v[82:85], v[174:177], v[166:169], v[70:73]
	v_mfma_f32_16x16x32_bf16 v[70:73], v[178:181], v[146:149], v[78:81]
	v_mfma_f32_16x16x32_bf16 v[66:69], v[162:165], v[170:173], v[66:69]
	v_mfma_f32_16x16x32_bf16 v[62:65], v[178:181], v[170:173], v[62:65]
	v_mfma_f32_16x16x32_bf16 v[10:13], v[162:165], v[46:49], v[114:117]
	v_mfma_f32_16x16x32_bf16 v[14:17], v[178:181], v[46:49], v[110:113]
	v_mfma_f32_16x16x32_bf16 v[46:49], v[162:165], v[130:133], v[98:101]
	v_mfma_f32_16x16x32_bf16 v[78:81], v[182:185], v[166:169], v[70:73]
	v_mfma_f32_16x16x32_bf16 v[66:69], v[174:177], v[190:193], v[66:69]
	v_mfma_f32_16x16x32_bf16 v[62:65], v[182:185], v[190:193], v[62:65]
	v_mfma_f32_16x16x32_bf16 v[10:13], v[174:177], v[126:129], v[10:13]
	v_mfma_f32_16x16x32_bf16 v[14:17], v[182:185], v[126:129], v[14:17]
	v_mfma_f32_16x16x32_bf16 v[46:49], v[174:177], v[142:145], v[46:49]
	s_add_i32 s65, 0, 0x18000
	v_add_u32_e32 v0, s65, v230
	s_barrier
	ds_read_b128 v[70:73], v0
	ds_read_b128 v[74:77], v0 offset:1024
	ds_read_b128 v[98:101], v0 offset:2048
	ds_read_b128 v[110:113], v0 offset:3072
	s_add_u32 s16, s16, 0x40000
	s_addc_u32 s17, s17, 0
	s_mov_b32 m0, s83
	v_lshl_add_u64 v[146:147], s[16:17], 0, v[206:207]
	ds_read_b128 v[114:117], v232 offset:32768
	ds_read_b128 v[126:129], v232 offset:33792
	ds_read_b128 v[130:133], v232 offset:34816
	ds_read_b128 v[142:145], v232 offset:35840
	ds_read_b128 v[162:165], v232 offset:36864
	ds_read_b128 v[174:177], v232 offset:37888
	ds_read_b128 v[218:221], v232 offset:38912
	ds_read_b128 v[234:237], v232 offset:39936
	global_load_lds_dwordx4 v[146:147], off
	s_mov_b32 m0, s84
	v_lshl_add_u64 v[146:147], s[16:17], 0, v[210:211]
	global_load_lds_dwordx4 v[146:147], off
	s_waitcnt lgkmcnt(8)
	s_barrier
	s_waitcnt lgkmcnt(0)
	v_mfma_f32_16x16x32_bf16 v[50:53], v[70:73], v[114:117], v[50:53]
	v_mfma_f32_16x16x32_bf16 v[202:205], v[74:77], v[126:129], v[50:53]
	v_mfma_f32_16x16x32_bf16 v[50:53], v[98:101], v[114:117], v[54:57]
	v_mfma_f32_16x16x32_bf16 v[198:201], v[110:113], v[126:129], v[50:53]
	v_mfma_f32_16x16x32_bf16 v[50:53], v[70:73], v[130:133], v[58:61]
	v_mfma_f32_16x16x32_bf16 v[182:185], v[74:77], v[142:145], v[50:53]
	v_mfma_f32_16x16x32_bf16 v[50:53], v[98:101], v[130:133], v[150:153]
	v_mfma_f32_16x16x32_bf16 v[178:181], v[110:113], v[142:145], v[50:53]
	v_mfma_f32_16x16x32_bf16 v[50:53], v[70:73], v[162:165], v[158:161]
	v_mfma_f32_16x16x32_bf16 v[158:161], v[74:77], v[174:177], v[50:53]
	v_mfma_f32_16x16x32_bf16 v[50:53], v[98:101], v[162:165], v[154:157]
	v_mfma_f32_16x16x32_bf16 v[154:157], v[110:113], v[174:177], v[50:53]
	v_mfma_f32_16x16x32_bf16 v[50:53], v[70:73], v[218:221], v[138:141]
	v_mfma_f32_16x16x32_bf16 v[138:141], v[74:77], v[234:237], v[50:53]
	v_mfma_f32_16x16x32_bf16 v[50:53], v[98:101], v[218:221], v[134:137]
	v_mfma_f32_16x16x32_bf16 v[134:137], v[110:113], v[234:237], v[50:53]
	s_barrier
	s_add_i32 s16, 0, 0x1c000
	s_add_i32 s17, s65, s22
	v_add_u32_e32 v0, s16, v230
	v_lshl_add_u64 v[146:147], v[222:223], 0, s[20:21]
	s_mov_b32 m0, s17
	ds_read_b128 v[50:53], v0
	ds_read_b128 v[54:57], v0 offset:1024
	ds_read_b128 v[58:61], v0 offset:2048
	ds_read_b128 v[150:153], v0 offset:3072
	global_load_lds_dwordx4 v[146:147], off
	s_add_i32 m0, s17, 0x2000
	v_lshl_add_u64 v[146:147], v[226:227], 0, s[20:21]
	global_load_lds_dwordx4 v[146:147], off
	s_barrier
	s_waitcnt lgkmcnt(0)
	v_mfma_f32_16x16x32_bf16 v[18:21], v[58:61], v[114:117], v[18:21]
	v_mfma_f32_16x16x32_bf16 v[190:193], v[150:153], v[126:129], v[18:21]
	v_mfma_f32_16x16x32_bf16 v[18:21], v[50:53], v[130:133], v[22:25]
	v_mfma_f32_16x16x32_bf16 v[170:173], v[54:57], v[142:145], v[18:21]
	v_mfma_f32_16x16x32_bf16 v[18:21], v[58:61], v[130:133], v[26:29]
	v_mfma_f32_16x16x32_bf16 v[146:149], v[50:53], v[114:117], v[186:189]
	v_mfma_f32_16x16x32_bf16 v[166:169], v[150:153], v[142:145], v[18:21]
	v_mfma_f32_16x16x32_bf16 v[18:21], v[50:53], v[162:165], v[30:33]
	v_mfma_f32_16x16x32_bf16 v[194:197], v[54:57], v[126:129], v[146:149]
	v_mfma_f32_16x16x32_bf16 v[146:149], v[54:57], v[174:177], v[18:21]
	v_mfma_f32_16x16x32_bf16 v[18:21], v[58:61], v[162:165], v[34:37]
	v_mfma_f32_16x16x32_bf16 v[142:145], v[150:153], v[174:177], v[18:21]
	v_mfma_f32_16x16x32_bf16 v[18:21], v[50:53], v[218:221], v[38:41]
	v_mfma_f32_16x16x32_bf16 v[130:133], v[54:57], v[234:237], v[18:21]
	v_mfma_f32_16x16x32_bf16 v[18:21], v[58:61], v[218:221], v[42:45]
	v_mfma_f32_16x16x32_bf16 v[126:129], v[150:153], v[234:237], v[18:21]
	s_mov_b32 m0, s91
	v_lshl_add_u64 v[114:115], v[238:239], 0, s[20:21]
	s_barrier
	s_nop 2
	ds_read_b128 v[18:21], v232 offset:49152
	ds_read_b128 v[22:25], v232 offset:50176
	ds_read_b128 v[26:29], v232 offset:51200
	ds_read_b128 v[30:33], v232 offset:52224
	ds_read_b128 v[34:37], v232 offset:53248
	ds_read_b128 v[38:41], v232 offset:54272
	ds_read_b128 v[42:45], v232 offset:55296
	ds_read_b128 v[162:165], v232 offset:56320
	global_load_lds_dwordx4 v[114:115], off
	s_mov_b32 m0, s59
	v_lshl_add_u64 v[114:115], v[240:241], 0, s[20:21]
	global_load_lds_dwordx4 v[114:115], off
	s_barrier
	s_waitcnt lgkmcnt(0)
	v_mfma_f32_16x16x32_bf16 v[114:117], v[70:73], v[18:21], v[122:125]
	v_mfma_f32_16x16x32_bf16 v[106:109], v[70:73], v[26:29], v[106:109]
	v_mfma_f32_16x16x32_bf16 v[90:93], v[70:73], v[34:37], v[90:93]
	v_mfma_f32_16x16x32_bf16 v[2:5], v[70:73], v[42:45], v[2:5]
	v_mfma_f32_16x16x32_bf16 v[122:125], v[74:77], v[22:25], v[114:117]
	v_mfma_f32_16x16x32_bf16 v[114:117], v[98:101], v[18:21], v[118:121]
	v_mfma_f32_16x16x32_bf16 v[106:109], v[74:77], v[30:33], v[106:109]
	v_mfma_f32_16x16x32_bf16 v[102:105], v[98:101], v[26:29], v[102:105]
	v_mfma_f32_16x16x32_bf16 v[90:93], v[74:77], v[38:41], v[90:93]
	v_mfma_f32_16x16x32_bf16 v[86:89], v[98:101], v[34:37], v[86:89]
	v_mfma_f32_16x16x32_bf16 v[74:77], v[74:77], v[162:165], v[2:5]
	v_mfma_f32_16x16x32_bf16 v[2:5], v[98:101], v[42:45], v[6:9]
	v_mfma_f32_16x16x32_bf16 v[118:121], v[110:113], v[22:25], v[114:117]
	v_mfma_f32_16x16x32_bf16 v[102:105], v[110:113], v[30:33], v[102:105]
	v_mfma_f32_16x16x32_bf16 v[86:89], v[110:113], v[38:41], v[86:89]
	v_mfma_f32_16x16x32_bf16 v[70:73], v[110:113], v[162:165], v[2:5]
	s_barrier
	s_add_u32 s14, s14, 0x40080
	s_addc_u32 s15, s15, 0
	s_add_i32 s16, s16, s22
	s_mov_b32 m0, s16
	v_lshl_add_u64 v[2:3], s[14:15], 0, v[208:209]
	global_load_lds_dwordx4 v[2:3], off
	s_add_i32 m0, s16, 0x2000
	v_lshl_add_u64 v[2:3], s[14:15], 0, v[212:213]
	global_load_lds_dwordx4 v[2:3], off
	s_waitcnt vmcnt(6)
	s_barrier
	v_mfma_f32_16x16x32_bf16 v[2:5], v[50:53], v[18:21], v[10:13]
	v_mfma_f32_16x16x32_bf16 v[114:117], v[54:57], v[22:25], v[2:5]
	v_mfma_f32_16x16x32_bf16 v[2:5], v[58:61], v[18:21], v[14:17]
	v_mfma_f32_16x16x32_bf16 v[110:113], v[150:153], v[22:25], v[2:5]
	v_mfma_f32_16x16x32_bf16 v[2:5], v[50:53], v[26:29], v[46:49]
	v_mfma_f32_16x16x32_bf16 v[98:101], v[54:57], v[30:33], v[2:5]
	v_mfma_f32_16x16x32_bf16 v[2:5], v[58:61], v[26:29], v[94:97]
	v_mfma_f32_16x16x32_bf16 v[94:97], v[150:153], v[30:33], v[2:5]
	v_mfma_f32_16x16x32_bf16 v[2:5], v[50:53], v[34:37], v[82:85]
	v_mfma_f32_16x16x32_bf16 v[82:85], v[54:57], v[38:41], v[2:5]
	v_mfma_f32_16x16x32_bf16 v[2:5], v[58:61], v[34:37], v[78:81]
	v_mfma_f32_16x16x32_bf16 v[78:81], v[150:153], v[38:41], v[2:5]
	v_mfma_f32_16x16x32_bf16 v[2:5], v[50:53], v[42:45], v[66:69]
	v_mfma_f32_16x16x32_bf16 v[66:69], v[54:57], v[162:165], v[2:5]
	v_mfma_f32_16x16x32_bf16 v[2:5], v[58:61], v[42:45], v[62:65]
	v_mfma_f32_16x16x32_bf16 v[62:65], v[150:153], v[162:165], v[2:5]
	s_add_i32 s64, s64, 2
	s_add_u32 s12, s12, 0x100
	s_addc_u32 s13, s13, 0
	s_add_u32 s62, s62, 0x100
	s_addc_u32 s63, s63, 0
	s_cmp_gt_u32 s64, 13
	s_barrier
	s_cbranch_scc0 .LBB0_491

.LBB0_660:
	v_cndmask_b32_e64 v2, 0, 1, s[4:5]
	s_andn2_b64 vcc, exec, s[36:37]
	v_cmp_ne_u32_e64 s[4:5], 1, v2
	s_cbranch_vccnz .LBB0_663
	v_lshl_add_u64 v[2:3], v[138:139], 0, s[0:1]
	s_add_i32 m0, s62, 0x7400
	s_and_b64 vcc, exec, s[4:5]
	global_load_lds_dwordx4 v[2:3], off
	s_add_i32 m0, s62, 0x9400
	v_lshl_add_u64 v[2:3], v[136:137], 0, s[0:1]
	global_load_lds_dwordx4 v[2:3], off
	s_add_i32 m0, s62, 0xb400
	v_lshl_add_u64 v[2:3], v[134:135], 0, s[0:1]
	global_load_lds_dwordx4 v[2:3], off
	s_cbranch_vccnz .LBB0_663
	s_add_i32 m0, s62, 0xd400
	v_lshl_add_u64 v[2:3], v[140:141], 0, s[0:1]
	global_load_lds_dwordx4 v[2:3], off
.LBB0_663:
	s_andn2_b64 vcc, exec, s[38:39]
	s_cbranch_vccnz .LBB0_666
	v_lshl_add_u64 v[2:3], v[138:139], 0, s[30:31]
	s_add_i32 m0, s62, 0xe800
	s_and_b64 vcc, exec, s[4:5]
	global_load_lds_dwordx4 v[2:3], off
	s_add_i32 m0, s62, 0x10800
	v_lshl_add_u64 v[2:3], v[136:137], 0, s[30:31]
	global_load_lds_dwordx4 v[2:3], off
	s_add_i32 m0, s62, 0x12800
	v_lshl_add_u64 v[2:3], v[134:135], 0, s[30:31]
	global_load_lds_dwordx4 v[2:3], off
	s_cbranch_vccnz .LBB0_666
	s_add_i32 m0, s62, 0x14800
	v_lshl_add_u64 v[2:3], v[140:141], 0, s[30:31]
	global_load_lds_dwordx4 v[2:3], off

.LBB0_702:
	s_ashr_i32 s7, s6, 31
	s_lshr_b32 s54, s7, 30
	s_add_i32 s54, s6, s54
	s_and_b32 s54, s54, 0x3ffffc
	s_sub_i32 s54, s6, s54
	s_mulk_i32 s54, 0x7400
	s_lshl_b64 s[6:7], s[6:7], 19
	s_add_i32 s54, s62, s54
	v_lshl_add_u64 v[114:115], v[138:139], 0, s[6:7]
	s_mov_b32 m0, s54
	s_and_b64 vcc, exec, s[4:5]
	global_load_lds_dwordx4 v[114:115], off
	s_add_i32 m0, s54, 0x2000
	v_lshl_add_u64 v[114:115], v[136:137], 0, s[6:7]
	global_load_lds_dwordx4 v[114:115], off
	s_add_i32 m0, s54, 0x4000
	v_lshl_add_u64 v[114:115], v[134:135], 0, s[6:7]
	global_load_lds_dwordx4 v[114:115], off
	s_cbranch_vccnz .LBB0_704
	s_add_i32 m0, s54, 0x6000
	v_lshl_add_u64 v[114:115], v[140:141], 0, s[6:7]
	global_load_lds_dwordx4 v[114:115], off

.LBB0_738:
	s_ashr_i32 s9, s8, 31
	s_lshl_b64 s[6:7], s[8:9], 13
	v_readlane_b32 s9, v254, 21
	s_add_u32 s26, s9, s6
	v_readlane_b32 s9, v254, 22
	s_addc_u32 s27, s9, s7
	s_lshl_b32 s40, s15, 8
	s_add_i32 s17, s40, 0
	v_lshlrev_b32_e32 v0, 2, v16
	s_add_i32 m0, s17, 0x5400
	s_lshl_b32 s9, s37, 2
	global_load_lds_dword v0, s[26:27]
	s_add_i32 s9, s9, 4
	v_cndmask_b32_e64 v2, 0, 1, s[4:5]
	v_lshl_add_u64 v[108:109], s[26:27], 0, v[0:1]
	s_cmp_lt_i32 s9, 2
	v_cmp_ne_u32_e64 s[4:5], 1, v2
	s_cbranch_scc1 .LBB0_742
	v_lshl_add_u64 v[2:3], v[104:105], 0, s[0:1]
	s_add_i32 m0, s12, 0x5c00
	s_and_b64 vcc, exec, s[4:5]
	global_load_lds_dwordx4 v[2:3], off
	s_add_i32 m0, s12, 0x7c00
	v_lshl_add_u64 v[2:3], v[102:103], 0, s[0:1]
	global_load_lds_dwordx4 v[2:3], off
	s_cbranch_vccnz .LBB0_741
	s_add_i32 m0, s12, 0x9c00
	v_lshl_add_u64 v[2:3], v[106:107], 0, s[0:1]
	global_load_lds_dwordx4 v[2:3], off
.LBB0_741:
	s_add_i32 m0, s17, 0xb000
	v_lshl_add_u64 v[2:3], v[108:109], 0, s[54:55]
	global_load_lds_dword v[2:3], off
.LBB0_742:
	s_cmp_lt_i32 s9, 3
	s_cbranch_scc1 .LBB0_746
	v_lshl_add_u64 v[2:3], v[104:105], 0, s[30:31]
	s_add_i32 m0, s12, 0xb800
	s_and_b64 vcc, exec, s[4:5]
	global_load_lds_dwordx4 v[2:3], off
	s_add_i32 m0, s12, 0xd800
	v_lshl_add_u64 v[2:3], v[102:103], 0, s[30:31]
	global_load_lds_dwordx4 v[2:3], off
	s_cbranch_vccnz .LBB0_745
	s_add_i32 m0, s12, 0xf800
	v_lshl_add_u64 v[2:3], v[106:107], 0, s[30:31]
	global_load_lds_dwordx4 v[2:3], off
.LBB0_745:
	s_mov_b64 s[12:13], 0x200
	s_add_i32 m0, s17, 0x10c00
	v_lshl_add_u64 v[2:3], v[108:109], 0, s[12:13]
	global_load_lds_dword v[2:3], off

.LBB0_783:
	s_ashr_i32 s7, s6, 31
	s_lshr_b32 s15, s7, 30
	s_add_i32 s15, s6, s15
	s_and_b32 s15, s15, 0x3ffffc
	s_sub_i32 s15, s6, s15
	s_mulk_i32 s15, 0x5c00
	s_add_i32 s26, s15, 0
	s_lshl_b64 s[6:7], s[6:7], 19
	s_add_i32 s15, s26, s39
	v_lshl_add_u64 v[82:83], v[104:105], 0, s[6:7]
	s_mov_b32 m0, s15
	s_and_b64 vcc, exec, s[4:5]
	global_load_lds_dwordx4 v[82:83], off
	s_add_i32 m0, s15, 0x2000
	v_lshl_add_u64 v[82:83], v[102:103], 0, s[6:7]
	global_load_lds_dwordx4 v[82:83], off
	s_cbranch_vccnz .LBB0_785
	s_add_i32 m0, s15, 0x4000
	v_lshl_add_u64 v[82:83], v[106:107], 0, s[6:7]
	global_load_lds_dwordx4 v[82:83], off
.LBB0_785:
	s_ashr_i32 s15, s14, 31
	s_add_i32 s6, s26, s40
	s_add_i32 m0, s6, 0x5400
	v_lshl_add_u64 v[82:83], s[14:15], 2, v[108:109]
	global_load_lds_dword v[82:83], off

.LBB0_860:
	s_add_u32 vcc_lo, s12, 0x100
	s_addc_u32 vcc_hi, s13, 0
	s_mov_b32 s8, 0
	s_add_i32 s63, s8, 2
	s_add_u32 s6, s10, 0x100
	s_addc_u32 s7, s11, 0
	s_add_i32 s77, 0, 0x10000
	v_add_u32_e32 v0, s77, v234
	ds_read_b128 v[2:5], v0
	ds_read_b128 v[6:9], v0 offset:1024
	ds_read_b128 v[10:13], v0 offset:2048
	ds_read_b128 v[14:17], v0 offset:3072
	s_cmp_eq_u32 s23, s8
	s_cselect_b32 s8, s38, s6
	s_cselect_b32 s9, s39, s7
	s_cselect_b32 s13, s41, vcc_hi
	s_cselect_b32 s12, s40, vcc_lo
	v_lshl_add_u64 v[50:51], s[10:11], 0, v[214:215]
	s_add_i32 m0, s56, 0xc000
	ds_read_b128 v[18:21], v237
	ds_read_b128 v[22:25], v237 offset:1024
	ds_read_b128 v[26:29], v237 offset:2048
	ds_read_b128 v[30:33], v237 offset:3072
	ds_read_b128 v[34:37], v237 offset:4096
	ds_read_b128 v[38:41], v237 offset:5120
	ds_read_b128 v[42:45], v237 offset:6144
	ds_read_b128 v[46:49], v237 offset:7168
	global_load_lds_dwordx4 v[50:51], off
	s_add_i32 m0, s56, 0xe000
	v_lshl_add_u64 v[50:51], s[10:11], 0, v[216:217]
	global_load_lds_dwordx4 v[50:51], off
	s_waitcnt lgkmcnt(8)
	s_barrier
	s_waitcnt lgkmcnt(0)
	v_mfma_f32_16x16x32_bf16 v[154:157], v[2:5], v[34:37], 0
	v_mfma_f32_16x16x32_bf16 v[150:153], v[10:13], v[34:37], 0
	v_mfma_f32_16x16x32_bf16 v[138:141], v[2:5], v[42:45], 0
	v_mfma_f32_16x16x32_bf16 v[134:137], v[10:13], v[42:45], 0
	v_mfma_f32_16x16x32_bf16 v[50:53], v[2:5], v[18:21], 0
	v_mfma_f32_16x16x32_bf16 v[54:57], v[10:13], v[18:21], 0
	v_mfma_f32_16x16x32_bf16 v[58:61], v[2:5], v[26:29], 0
	v_mfma_f32_16x16x32_bf16 v[166:169], v[10:13], v[26:29], 0
	v_mfma_f32_16x16x32_bf16 v[154:157], v[6:9], v[38:41], v[154:157]
	v_mfma_f32_16x16x32_bf16 v[150:153], v[14:17], v[38:41], v[150:153]
	v_mfma_f32_16x16x32_bf16 v[138:141], v[6:9], v[46:49], v[138:141]
	v_mfma_f32_16x16x32_bf16 v[134:137], v[14:17], v[46:49], v[134:137]
	v_mfma_f32_16x16x32_bf16 v[50:53], v[6:9], v[22:25], v[50:53]
	v_mfma_f32_16x16x32_bf16 v[54:57], v[14:17], v[22:25], v[54:57]
	v_mfma_f32_16x16x32_bf16 v[58:61], v[6:9], v[30:33], v[58:61]
	v_mfma_f32_16x16x32_bf16 v[166:169], v[14:17], v[30:33], v[166:169]
	s_barrier
	s_add_i32 s80, 0, 0x14000
	s_add_i32 s10, s77, s53
	v_add_u32_e32 v0, s80, v234
	v_lshl_add_u64 v[222:223], s[12:13], 0, v[208:209]
	s_mov_b32 m0, s10
	ds_read_b128 v[170:173], v0
	ds_read_b128 v[174:177], v0 offset:1024
	ds_read_b128 v[178:181], v0 offset:2048
	ds_read_b128 v[190:193], v0 offset:3072
	global_load_lds_dwordx4 v[222:223], off
	s_add_i32 m0, s10, 0x2000
	v_lshl_add_u64 v[226:227], s[12:13], 0, v[212:213]
	global_load_lds_dwordx4 v[226:227], off
	s_barrier
	s_waitcnt lgkmcnt(0)
	v_mfma_f32_16x16x32_bf16 v[186:189], v[170:173], v[18:21], 0
	v_mfma_f32_16x16x32_bf16 v[18:21], v[178:181], v[18:21], 0
	v_mfma_f32_16x16x32_bf16 v[186:189], v[174:177], v[22:25], v[186:189]
	v_mfma_f32_16x16x32_bf16 v[18:21], v[190:193], v[22:25], v[18:21]
	v_mfma_f32_16x16x32_bf16 v[22:25], v[170:173], v[26:29], 0
	v_mfma_f32_16x16x32_bf16 v[26:29], v[178:181], v[26:29], 0
	v_mfma_f32_16x16x32_bf16 v[22:25], v[174:177], v[30:33], v[22:25]
	v_mfma_f32_16x16x32_bf16 v[26:29], v[190:193], v[30:33], v[26:29]
	v_mfma_f32_16x16x32_bf16 v[30:33], v[170:173], v[34:37], 0
	v_mfma_f32_16x16x32_bf16 v[34:37], v[178:181], v[34:37], 0
	v_mfma_f32_16x16x32_bf16 v[30:33], v[174:177], v[38:41], v[30:33]
	v_mfma_f32_16x16x32_bf16 v[34:37], v[190:193], v[38:41], v[34:37]
	v_mfma_f32_16x16x32_bf16 v[38:41], v[170:173], v[42:45], 0
	v_mfma_f32_16x16x32_bf16 v[42:45], v[178:181], v[42:45], 0
	v_mfma_f32_16x16x32_bf16 v[38:41], v[174:177], v[46:49], v[38:41]
	v_mfma_f32_16x16x32_bf16 v[42:45], v[190:193], v[46:49], v[42:45]
	s_mov_b32 m0, s56
	v_lshl_add_u64 v[228:229], s[8:9], 0, v[206:207]
	s_barrier
	ds_read_b128 v[46:49], v237 offset:16384
	ds_read_b128 v[126:129], v237 offset:17408
	ds_read_b128 v[130:133], v237 offset:18432
	ds_read_b128 v[142:145], v237 offset:19456
	ds_read_b128 v[146:149], v237 offset:20480
	ds_read_b128 v[158:161], v237 offset:21504
	ds_read_b128 v[162:165], v237 offset:22528
	ds_read_b128 v[182:185], v237 offset:23552
	global_load_lds_dwordx4 v[228:229], off
	s_mov_b32 m0, s57
	v_lshl_add_u64 v[230:231], s[8:9], 0, v[210:211]
	global_load_lds_dwordx4 v[230:231], off
	s_barrier
	s_waitcnt lgkmcnt(0)
	v_mfma_f32_16x16x32_bf16 v[122:125], v[2:5], v[46:49], 0
	v_mfma_f32_16x16x32_bf16 v[118:121], v[10:13], v[46:49], 0
	v_mfma_f32_16x16x32_bf16 v[110:113], v[2:5], v[130:133], 0
	v_mfma_f32_16x16x32_bf16 v[102:105], v[10:13], v[130:133], 0
	v_mfma_f32_16x16x32_bf16 v[94:97], v[2:5], v[146:149], 0
	v_mfma_f32_16x16x32_bf16 v[86:89], v[10:13], v[146:149], 0
	v_mfma_f32_16x16x32_bf16 v[2:5], v[2:5], v[162:165], 0
	v_mfma_f32_16x16x32_bf16 v[122:125], v[6:9], v[126:129], v[122:125]
	v_mfma_f32_16x16x32_bf16 v[118:121], v[14:17], v[126:129], v[118:121]
	v_mfma_f32_16x16x32_bf16 v[110:113], v[6:9], v[142:145], v[110:113]
	v_mfma_f32_16x16x32_bf16 v[102:105], v[14:17], v[142:145], v[102:105]
	v_mfma_f32_16x16x32_bf16 v[94:97], v[6:9], v[158:161], v[94:97]
	v_mfma_f32_16x16x32_bf16 v[86:89], v[14:17], v[158:161], v[86:89]
	v_mfma_f32_16x16x32_bf16 v[2:5], v[6:9], v[182:185], v[2:5]
	v_mfma_f32_16x16x32_bf16 v[6:9], v[10:13], v[162:165], 0
	v_mfma_f32_16x16x32_bf16 v[6:9], v[14:17], v[182:185], v[6:9]
	s_barrier
	s_add_u32 s10, s12, s73
	s_addc_u32 s11, s13, 0
	s_add_i32 s12, s80, s53
	v_lshl_add_u64 v[238:239], s[10:11], 0, v[208:209]
	s_mov_b32 m0, s12
	v_lshl_add_u64 v[240:241], s[10:11], 0, v[212:213]
	global_load_lds_dwordx4 v[238:239], off
	s_add_i32 m0, s12, 0x2000
	s_nop 0
	global_load_lds_dwordx4 v[240:241], off
	s_waitcnt vmcnt(6)
	s_barrier
	v_mfma_f32_16x16x32_bf16 v[70:73], v[178:181], v[130:133], 0
	v_mfma_f32_16x16x32_bf16 v[90:93], v[190:193], v[142:145], v[70:73]
	v_mfma_f32_16x16x32_bf16 v[70:73], v[170:173], v[146:149], 0
	v_mfma_f32_16x16x32_bf16 v[82:85], v[174:177], v[158:161], v[70:73]
	v_mfma_f32_16x16x32_bf16 v[70:73], v[178:181], v[146:149], 0
	v_mfma_f32_16x16x32_bf16 v[66:69], v[170:173], v[162:165], 0
	v_mfma_f32_16x16x32_bf16 v[62:65], v[178:181], v[162:165], 0
	v_mfma_f32_16x16x32_bf16 v[10:13], v[170:173], v[46:49], 0
	v_mfma_f32_16x16x32_bf16 v[14:17], v[178:181], v[46:49], 0
	v_mfma_f32_16x16x32_bf16 v[46:49], v[170:173], v[130:133], 0
	v_mfma_f32_16x16x32_bf16 v[74:77], v[190:193], v[158:161], v[70:73]
	v_mfma_f32_16x16x32_bf16 v[66:69], v[174:177], v[182:185], v[66:69]
	v_mfma_f32_16x16x32_bf16 v[62:65], v[190:193], v[182:185], v[62:65]
	v_mfma_f32_16x16x32_bf16 v[10:13], v[174:177], v[126:129], v[10:13]
	v_mfma_f32_16x16x32_bf16 v[14:17], v[190:193], v[126:129], v[14:17]
	v_mfma_f32_16x16x32_bf16 v[46:49], v[174:177], v[142:145], v[46:49]
	s_add_i32 s10, 0, 0x18000
	v_add_u32_e32 v0, s10, v234
	s_barrier
	ds_read_b128 v[70:73], v0
	ds_read_b128 v[78:81], v0 offset:1024
	ds_read_b128 v[98:101], v0 offset:2048
	ds_read_b128 v[106:109], v0 offset:3072
	s_add_u32 s8, s8, 0xa0000
	s_addc_u32 s9, s9, 0
	s_mov_b32 m0, s58
	v_lshl_add_u64 v[146:147], s[8:9], 0, v[206:207]
	ds_read_b128 v[114:117], v237 offset:32768
	ds_read_b128 v[126:129], v237 offset:33792
	ds_read_b128 v[130:133], v237 offset:34816
	ds_read_b128 v[142:145], v237 offset:35840
	ds_read_b128 v[174:177], v237 offset:36864
	ds_read_b128 v[190:193], v237 offset:37888
	ds_read_b128 v[194:197], v237 offset:38912
	ds_read_b128 v[218:221], v237 offset:39936
	global_load_lds_dwordx4 v[146:147], off
	s_mov_b32 m0, s59
	v_lshl_add_u64 v[146:147], s[8:9], 0, v[210:211]
	global_load_lds_dwordx4 v[146:147], off
	s_waitcnt lgkmcnt(8)
	s_barrier
	s_waitcnt lgkmcnt(0)
	v_mfma_f32_16x16x32_bf16 v[50:53], v[70:73], v[114:117], v[50:53]
	v_mfma_f32_16x16x32_bf16 v[202:205], v[78:81], v[126:129], v[50:53]
	v_mfma_f32_16x16x32_bf16 v[50:53], v[98:101], v[114:117], v[54:57]
	v_mfma_f32_16x16x32_bf16 v[198:201], v[106:109], v[126:129], v[50:53]
	v_mfma_f32_16x16x32_bf16 v[50:53], v[70:73], v[130:133], v[58:61]
	v_mfma_f32_16x16x32_bf16 v[178:181], v[78:81], v[142:145], v[50:53]
	v_mfma_f32_16x16x32_bf16 v[50:53], v[98:101], v[130:133], v[166:169]
	v_mfma_f32_16x16x32_bf16 v[170:173], v[106:109], v[142:145], v[50:53]
	v_mfma_f32_16x16x32_bf16 v[50:53], v[70:73], v[174:177], v[154:157]
	v_mfma_f32_16x16x32_bf16 v[154:157], v[78:81], v[190:193], v[50:53]
	v_mfma_f32_16x16x32_bf16 v[50:53], v[98:101], v[174:177], v[150:153]
	v_mfma_f32_16x16x32_bf16 v[150:153], v[106:109], v[190:193], v[50:53]
	v_mfma_f32_16x16x32_bf16 v[50:53], v[70:73], v[194:197], v[138:141]
	v_mfma_f32_16x16x32_bf16 v[138:141], v[78:81], v[218:221], v[50:53]
	v_mfma_f32_16x16x32_bf16 v[50:53], v[98:101], v[194:197], v[134:137]
	v_mfma_f32_16x16x32_bf16 v[134:137], v[106:109], v[218:221], v[50:53]
	s_barrier
	s_add_i32 s8, 0, 0x1c000
	s_add_i32 s9, s10, s53
	v_add_u32_e32 v0, s8, v234
	v_lshl_add_u64 v[146:147], v[222:223], 0, s[20:21]
	s_mov_b32 m0, s9
	ds_read_b128 v[50:53], v0
	ds_read_b128 v[54:57], v0 offset:1024
	ds_read_b128 v[58:61], v0 offset:2048
	ds_read_b128 v[166:169], v0 offset:3072
	global_load_lds_dwordx4 v[146:147], off
	s_add_i32 m0, s9, 0x2000
	v_lshl_add_u64 v[146:147], v[226:227], 0, s[20:21]
	global_load_lds_dwordx4 v[146:147], off
	s_barrier
	s_waitcnt lgkmcnt(0)
	v_mfma_f32_16x16x32_bf16 v[18:21], v[58:61], v[114:117], v[18:21]
	v_mfma_f32_16x16x32_bf16 v[182:185], v[166:169], v[126:129], v[18:21]
	v_mfma_f32_16x16x32_bf16 v[18:21], v[50:53], v[130:133], v[22:25]
	v_mfma_f32_16x16x32_bf16 v[162:165], v[54:57], v[142:145], v[18:21]
	v_mfma_f32_16x16x32_bf16 v[18:21], v[58:61], v[130:133], v[26:29]
	v_mfma_f32_16x16x32_bf16 v[146:149], v[50:53], v[114:117], v[186:189]
	v_mfma_f32_16x16x32_bf16 v[158:161], v[166:169], v[142:145], v[18:21]
	v_mfma_f32_16x16x32_bf16 v[18:21], v[50:53], v[174:177], v[30:33]
	v_mfma_f32_16x16x32_bf16 v[186:189], v[54:57], v[126:129], v[146:149]
	v_mfma_f32_16x16x32_bf16 v[146:149], v[54:57], v[190:193], v[18:21]
	v_mfma_f32_16x16x32_bf16 v[18:21], v[58:61], v[174:177], v[34:37]
	v_mfma_f32_16x16x32_bf16 v[142:145], v[166:169], v[190:193], v[18:21]
	v_mfma_f32_16x16x32_bf16 v[18:21], v[50:53], v[194:197], v[38:41]
	v_mfma_f32_16x16x32_bf16 v[130:133], v[54:57], v[218:221], v[18:21]
	v_mfma_f32_16x16x32_bf16 v[18:21], v[58:61], v[194:197], v[42:45]
	v_mfma_f32_16x16x32_bf16 v[126:129], v[166:169], v[218:221], v[18:21]
	s_mov_b32 m0, s72
	v_lshl_add_u64 v[114:115], v[228:229], 0, s[20:21]
	s_barrier
	s_nop 2
	ds_read_b128 v[18:21], v237 offset:49152
	ds_read_b128 v[22:25], v237 offset:50176
	ds_read_b128 v[26:29], v237 offset:51200
	ds_read_b128 v[30:33], v237 offset:52224
	ds_read_b128 v[34:37], v237 offset:53248
	ds_read_b128 v[38:41], v237 offset:54272
	ds_read_b128 v[42:45], v237 offset:55296
	ds_read_b128 v[174:177], v237 offset:56320
	global_load_lds_dwordx4 v[114:115], off
	s_mov_b32 m0, s22
	v_lshl_add_u64 v[114:115], v[230:231], 0, s[20:21]
	global_load_lds_dwordx4 v[114:115], off
	s_barrier
	s_waitcnt lgkmcnt(0)
	v_mfma_f32_16x16x32_bf16 v[114:117], v[70:73], v[18:21], v[122:125]
	v_mfma_f32_16x16x32_bf16 v[110:113], v[70:73], v[26:29], v[110:113]
	v_mfma_f32_16x16x32_bf16 v[94:97], v[70:73], v[34:37], v[94:97]
	v_mfma_f32_16x16x32_bf16 v[2:5], v[70:73], v[42:45], v[2:5]
	v_mfma_f32_16x16x32_bf16 v[122:125], v[78:81], v[22:25], v[114:117]
	v_mfma_f32_16x16x32_bf16 v[114:117], v[98:101], v[18:21], v[118:121]
	v_mfma_f32_16x16x32_bf16 v[110:113], v[78:81], v[30:33], v[110:113]
	v_mfma_f32_16x16x32_bf16 v[102:105], v[98:101], v[26:29], v[102:105]
	v_mfma_f32_16x16x32_bf16 v[94:97], v[78:81], v[38:41], v[94:97]
	v_mfma_f32_16x16x32_bf16 v[86:89], v[98:101], v[34:37], v[86:89]
	v_mfma_f32_16x16x32_bf16 v[78:81], v[78:81], v[174:177], v[2:5]
	v_mfma_f32_16x16x32_bf16 v[2:5], v[98:101], v[42:45], v[6:9]
	v_mfma_f32_16x16x32_bf16 v[118:121], v[106:109], v[22:25], v[114:117]
	v_mfma_f32_16x16x32_bf16 v[102:105], v[106:109], v[30:33], v[102:105]
	v_mfma_f32_16x16x32_bf16 v[86:89], v[106:109], v[38:41], v[86:89]
	v_mfma_f32_16x16x32_bf16 v[70:73], v[106:109], v[174:177], v[2:5]
	s_barrier
	s_add_i32 s8, s8, s53
	s_nop 0
	s_mov_b32 m0, s8
	v_lshl_add_u64 v[2:3], v[238:239], 0, s[20:21]
	global_load_lds_dwordx4 v[2:3], off
	s_add_i32 m0, s8, 0x2000
	v_lshl_add_u64 v[2:3], v[240:241], 0, s[20:21]
	global_load_lds_dwordx4 v[2:3], off
	s_waitcnt vmcnt(6)
	s_barrier
	v_mfma_f32_16x16x32_bf16 v[2:5], v[50:53], v[18:21], v[10:13]
	v_mfma_f32_16x16x32_bf16 v[114:117], v[54:57], v[22:25], v[2:5]
	v_mfma_f32_16x16x32_bf16 v[2:5], v[58:61], v[18:21], v[14:17]
	v_mfma_f32_16x16x32_bf16 v[106:109], v[166:169], v[22:25], v[2:5]
	v_mfma_f32_16x16x32_bf16 v[2:5], v[50:53], v[26:29], v[46:49]
	v_mfma_f32_16x16x32_bf16 v[98:101], v[54:57], v[30:33], v[2:5]
	v_mfma_f32_16x16x32_bf16 v[2:5], v[58:61], v[26:29], v[90:93]
	v_mfma_f32_16x16x32_bf16 v[90:93], v[166:169], v[30:33], v[2:5]
	v_mfma_f32_16x16x32_bf16 v[2:5], v[50:53], v[34:37], v[82:85]
	v_mfma_f32_16x16x32_bf16 v[82:85], v[54:57], v[38:41], v[2:5]
	v_mfma_f32_16x16x32_bf16 v[2:5], v[58:61], v[34:37], v[74:77]
	v_mfma_f32_16x16x32_bf16 v[74:77], v[166:169], v[38:41], v[2:5]
	v_mfma_f32_16x16x32_bf16 v[2:5], v[50:53], v[42:45], v[66:69]
	v_mfma_f32_16x16x32_bf16 v[66:69], v[54:57], v[174:177], v[2:5]
	v_mfma_f32_16x16x32_bf16 v[2:5], v[58:61], v[42:45], v[62:65]
	v_mfma_f32_16x16x32_bf16 v[62:65], v[166:169], v[174:177], v[2:5]
	s_add_u32 vcc_lo, vcc_lo, 0x100
	s_addc_u32 vcc_hi, vcc_hi, 0
	s_cmp_ge_u32 s63, s91
	s_mov_b64 s[10:11], s[6:7]
	s_mov_b32 s8, s63
	s_barrier
	s_cbranch_scc0 .LBB0_861
	s_branch .Lpeel_exit_g2
.LBB0_861:
	s_add_i32 s63, s8, 2
	s_add_u32 s6, s10, 0x100
	s_addc_u32 s7, s11, 0
	s_add_i32 s77, 0, 0x10000
	v_add_u32_e32 v0, s77, v234
	ds_read_b128 v[2:5], v0
	ds_read_b128 v[6:9], v0 offset:1024
	ds_read_b128 v[10:13], v0 offset:2048
	ds_read_b128 v[14:17], v0 offset:3072
	s_cmp_eq_u32 s23, s8
	s_cselect_b32 s8, s38, s6
	s_cselect_b32 s9, s39, s7
	s_cselect_b32 s13, s41, vcc_hi
	s_cselect_b32 s12, s40, vcc_lo
	v_lshl_add_u64 v[50:51], s[10:11], 0, v[214:215]
	s_add_i32 m0, s56, 0xc000
	ds_read_b128 v[18:21], v237
	ds_read_b128 v[22:25], v237 offset:1024
	ds_read_b128 v[26:29], v237 offset:2048
	ds_read_b128 v[30:33], v237 offset:3072
	ds_read_b128 v[34:37], v237 offset:4096
	ds_read_b128 v[38:41], v237 offset:5120
	ds_read_b128 v[42:45], v237 offset:6144
	ds_read_b128 v[46:49], v237 offset:7168
	global_load_lds_dwordx4 v[50:51], off
	s_add_i32 m0, s56, 0xe000
	v_lshl_add_u64 v[50:51], s[10:11], 0, v[216:217]
	global_load_lds_dwordx4 v[50:51], off
	s_waitcnt lgkmcnt(8)
	s_barrier
	s_waitcnt lgkmcnt(0)
	v_mfma_f32_16x16x32_bf16 v[154:157], v[2:5], v[34:37], v[154:157]
	v_mfma_f32_16x16x32_bf16 v[150:153], v[10:13], v[34:37], v[150:153]
	v_mfma_f32_16x16x32_bf16 v[138:141], v[2:5], v[42:45], v[138:141]
	v_mfma_f32_16x16x32_bf16 v[134:137], v[10:13], v[42:45], v[134:137]
	v_mfma_f32_16x16x32_bf16 v[50:53], v[2:5], v[18:21], v[202:205]
	v_mfma_f32_16x16x32_bf16 v[54:57], v[10:13], v[18:21], v[198:201]
	v_mfma_f32_16x16x32_bf16 v[58:61], v[2:5], v[26:29], v[178:181]
	v_mfma_f32_16x16x32_bf16 v[166:169], v[10:13], v[26:29], v[170:173]
	v_mfma_f32_16x16x32_bf16 v[154:157], v[6:9], v[38:41], v[154:157]
	v_mfma_f32_16x16x32_bf16 v[150:153], v[14:17], v[38:41], v[150:153]
	v_mfma_f32_16x16x32_bf16 v[138:141], v[6:9], v[46:49], v[138:141]
	v_mfma_f32_16x16x32_bf16 v[134:137], v[14:17], v[46:49], v[134:137]
	v_mfma_f32_16x16x32_bf16 v[50:53], v[6:9], v[22:25], v[50:53]
	v_mfma_f32_16x16x32_bf16 v[54:57], v[14:17], v[22:25], v[54:57]
	v_mfma_f32_16x16x32_bf16 v[58:61], v[6:9], v[30:33], v[58:61]
	v_mfma_f32_16x16x32_bf16 v[166:169], v[14:17], v[30:33], v[166:169]
	s_barrier
	s_add_i32 s80, 0, 0x14000
	s_add_i32 s10, s77, s53
	v_add_u32_e32 v0, s80, v234
	v_lshl_add_u64 v[222:223], s[12:13], 0, v[208:209]
	s_mov_b32 m0, s10
	ds_read_b128 v[170:173], v0
	ds_read_b128 v[174:177], v0 offset:1024
	ds_read_b128 v[178:181], v0 offset:2048
	ds_read_b128 v[190:193], v0 offset:3072
	global_load_lds_dwordx4 v[222:223], off
	s_add_i32 m0, s10, 0x2000
	v_lshl_add_u64 v[226:227], s[12:13], 0, v[212:213]
	global_load_lds_dwordx4 v[226:227], off
	s_barrier
	s_waitcnt lgkmcnt(0)
	v_mfma_f32_16x16x32_bf16 v[186:189], v[170:173], v[18:21], v[186:189]
	v_mfma_f32_16x16x32_bf16 v[18:21], v[178:181], v[18:21], v[182:185]
	v_mfma_f32_16x16x32_bf16 v[186:189], v[174:177], v[22:25], v[186:189]
	v_mfma_f32_16x16x32_bf16 v[18:21], v[190:193], v[22:25], v[18:21]
	v_mfma_f32_16x16x32_bf16 v[22:25], v[170:173], v[26:29], v[162:165]
	v_mfma_f32_16x16x32_bf16 v[26:29], v[178:181], v[26:29], v[158:161]
	v_mfma_f32_16x16x32_bf16 v[22:25], v[174:177], v[30:33], v[22:25]
	v_mfma_f32_16x16x32_bf16 v[26:29], v[190:193], v[30:33], v[26:29]
	v_mfma_f32_16x16x32_bf16 v[30:33], v[170:173], v[34:37], v[146:149]
	v_mfma_f32_16x16x32_bf16 v[34:37], v[178:181], v[34:37], v[142:145]
	v_mfma_f32_16x16x32_bf16 v[30:33], v[174:177], v[38:41], v[30:33]
	v_mfma_f32_16x16x32_bf16 v[34:37], v[190:193], v[38:41], v[34:37]
	v_mfma_f32_16x16x32_bf16 v[38:41], v[170:173], v[42:45], v[130:133]
	v_mfma_f32_16x16x32_bf16 v[42:45], v[178:181], v[42:45], v[126:129]
	v_mfma_f32_16x16x32_bf16 v[38:41], v[174:177], v[46:49], v[38:41]
	v_mfma_f32_16x16x32_bf16 v[42:45], v[190:193], v[46:49], v[42:45]
	s_mov_b32 m0, s56
	v_lshl_add_u64 v[228:229], s[8:9], 0, v[206:207]
	s_barrier
	ds_read_b128 v[46:49], v237 offset:16384
	ds_read_b128 v[126:129], v237 offset:17408
	ds_read_b128 v[130:133], v237 offset:18432
	ds_read_b128 v[142:145], v237 offset:19456
	ds_read_b128 v[146:149], v237 offset:20480
	ds_read_b128 v[158:161], v237 offset:21504
	ds_read_b128 v[162:165], v237 offset:22528
	ds_read_b128 v[182:185], v237 offset:23552
	global_load_lds_dwordx4 v[228:229], off
	s_mov_b32 m0, s57
	v_lshl_add_u64 v[230:231], s[8:9], 0, v[210:211]
	global_load_lds_dwordx4 v[230:231], off
	s_barrier
	s_waitcnt lgkmcnt(0)
	v_mfma_f32_16x16x32_bf16 v[122:125], v[2:5], v[46:49], v[122:125]
	v_mfma_f32_16x16x32_bf16 v[118:121], v[10:13], v[46:49], v[118:121]
	v_mfma_f32_16x16x32_bf16 v[110:113], v[2:5], v[130:133], v[110:113]
	v_mfma_f32_16x16x32_bf16 v[102:105], v[10:13], v[130:133], v[102:105]
	v_mfma_f32_16x16x32_bf16 v[94:97], v[2:5], v[146:149], v[94:97]
	v_mfma_f32_16x16x32_bf16 v[86:89], v[10:13], v[146:149], v[86:89]
	v_mfma_f32_16x16x32_bf16 v[2:5], v[2:5], v[162:165], v[78:81]
	v_mfma_f32_16x16x32_bf16 v[122:125], v[6:9], v[126:129], v[122:125]
	v_mfma_f32_16x16x32_bf16 v[118:121], v[14:17], v[126:129], v[118:121]
	v_mfma_f32_16x16x32_bf16 v[110:113], v[6:9], v[142:145], v[110:113]
	v_mfma_f32_16x16x32_bf16 v[102:105], v[14:17], v[142:145], v[102:105]
	v_mfma_f32_16x16x32_bf16 v[94:97], v[6:9], v[158:161], v[94:97]
	v_mfma_f32_16x16x32_bf16 v[86:89], v[14:17], v[158:161], v[86:89]
	v_mfma_f32_16x16x32_bf16 v[2:5], v[6:9], v[182:185], v[2:5]
	v_mfma_f32_16x16x32_bf16 v[6:9], v[10:13], v[162:165], v[70:73]
	v_mfma_f32_16x16x32_bf16 v[6:9], v[14:17], v[182:185], v[6:9]
	s_barrier
	s_add_u32 s10, s12, s73
	s_addc_u32 s11, s13, 0
	s_add_i32 s12, s80, s53
	v_lshl_add_u64 v[238:239], s[10:11], 0, v[208:209]
	s_mov_b32 m0, s12
	v_lshl_add_u64 v[240:241], s[10:11], 0, v[212:213]
	global_load_lds_dwordx4 v[238:239], off
	s_add_i32 m0, s12, 0x2000
	s_nop 0
	global_load_lds_dwordx4 v[240:241], off
	s_waitcnt vmcnt(6)
	s_barrier
	v_mfma_f32_16x16x32_bf16 v[70:73], v[178:181], v[130:133], v[90:93]
	v_mfma_f32_16x16x32_bf16 v[90:93], v[190:193], v[142:145], v[70:73]
	v_mfma_f32_16x16x32_bf16 v[70:73], v[170:173], v[146:149], v[82:85]
	v_mfma_f32_16x16x32_bf16 v[82:85], v[174:177], v[158:161], v[70:73]
	v_mfma_f32_16x16x32_bf16 v[70:73], v[178:181], v[146:149], v[74:77]
	v_mfma_f32_16x16x32_bf16 v[66:69], v[170:173], v[162:165], v[66:69]
	v_mfma_f32_16x16x32_bf16 v[62:65], v[178:181], v[162:165], v[62:65]
	v_mfma_f32_16x16x32_bf16 v[10:13], v[170:173], v[46:49], v[114:117]
	v_mfma_f32_16x16x32_bf16 v[14:17], v[178:181], v[46:49], v[106:109]
	v_mfma_f32_16x16x32_bf16 v[46:49], v[170:173], v[130:133], v[98:101]
	v_mfma_f32_16x16x32_bf16 v[74:77], v[190:193], v[158:161], v[70:73]
	v_mfma_f32_16x16x32_bf16 v[66:69], v[174:177], v[182:185], v[66:69]
	v_mfma_f32_16x16x32_bf16 v[62:65], v[190:193], v[182:185], v[62:65]
	v_mfma_f32_16x16x32_bf16 v[10:13], v[174:177], v[126:129], v[10:13]
	v_mfma_f32_16x16x32_bf16 v[14:17], v[190:193], v[126:129], v[14:17]
	v_mfma_f32_16x16x32_bf16 v[46:49], v[174:177], v[142:145], v[46:49]
	s_add_i32 s10, 0, 0x18000
	v_add_u32_e32 v0, s10, v234
	s_barrier
	ds_read_b128 v[70:73], v0
	ds_read_b128 v[78:81], v0 offset:1024
	ds_read_b128 v[98:101], v0 offset:2048
	ds_read_b128 v[106:109], v0 offset:3072
	s_add_u32 s8, s8, 0xa0000
	s_addc_u32 s9, s9, 0
	s_mov_b32 m0, s58
	v_lshl_add_u64 v[146:147], s[8:9], 0, v[206:207]
	ds_read_b128 v[114:117], v237 offset:32768
	ds_read_b128 v[126:129], v237 offset:33792
	ds_read_b128 v[130:133], v237 offset:34816
	ds_read_b128 v[142:145], v237 offset:35840
	ds_read_b128 v[174:177], v237 offset:36864
	ds_read_b128 v[190:193], v237 offset:37888
	ds_read_b128 v[194:197], v237 offset:38912
	ds_read_b128 v[218:221], v237 offset:39936
	global_load_lds_dwordx4 v[146:147], off
	s_mov_b32 m0, s59
	v_lshl_add_u64 v[146:147], s[8:9], 0, v[210:211]
	global_load_lds_dwordx4 v[146:147], off
	s_waitcnt lgkmcnt(8)
	s_barrier
	s_waitcnt lgkmcnt(0)
	v_mfma_f32_16x16x32_bf16 v[50:53], v[70:73], v[114:117], v[50:53]
	v_mfma_f32_16x16x32_bf16 v[202:205], v[78:81], v[126:129], v[50:53]
	v_mfma_f32_16x16x32_bf16 v[50:53], v[98:101], v[114:117], v[54:57]
	v_mfma_f32_16x16x32_bf16 v[198:201], v[106:109], v[126:129], v[50:53]
	v_mfma_f32_16x16x32_bf16 v[50:53], v[70:73], v[130:133], v[58:61]
	v_mfma_f32_16x16x32_bf16 v[178:181], v[78:81], v[142:145], v[50:53]
	v_mfma_f32_16x16x32_bf16 v[50:53], v[98:101], v[130:133], v[166:169]
	v_mfma_f32_16x16x32_bf16 v[170:173], v[106:109], v[142:145], v[50:53]
	v_mfma_f32_16x16x32_bf16 v[50:53], v[70:73], v[174:177], v[154:157]
	v_mfma_f32_16x16x32_bf16 v[154:157], v[78:81], v[190:193], v[50:53]
	v_mfma_f32_16x16x32_bf16 v[50:53], v[98:101], v[174:177], v[150:153]
	v_mfma_f32_16x16x32_bf16 v[150:153], v[106:109], v[190:193], v[50:53]
	v_mfma_f32_16x16x32_bf16 v[50:53], v[70:73], v[194:197], v[138:141]
	v_mfma_f32_16x16x32_bf16 v[138:141], v[78:81], v[218:221], v[50:53]
	v_mfma_f32_16x16x32_bf16 v[50:53], v[98:101], v[194:197], v[134:137]
	v_mfma_f32_16x16x32_bf16 v[134:137], v[106:109], v[218:221], v[50:53]
	s_barrier
	s_add_i32 s8, 0, 0x1c000
	s_add_i32 s9, s10, s53
	v_add_u32_e32 v0, s8, v234
	v_lshl_add_u64 v[146:147], v[222:223], 0, s[20:21]
	s_mov_b32 m0, s9
	ds_read_b128 v[50:53], v0
	ds_read_b128 v[54:57], v0 offset:1024
	ds_read_b128 v[58:61], v0 offset:2048
	ds_read_b128 v[166:169], v0 offset:3072
	global_load_lds_dwordx4 v[146:147], off
	s_add_i32 m0, s9, 0x2000
	v_lshl_add_u64 v[146:147], v[226:227], 0, s[20:21]
	global_load_lds_dwordx4 v[146:147], off
	s_barrier
	s_waitcnt lgkmcnt(0)
	v_mfma_f32_16x16x32_bf16 v[18:21], v[58:61], v[114:117], v[18:21]
	v_mfma_f32_16x16x32_bf16 v[182:185], v[166:169], v[126:129], v[18:21]
	v_mfma_f32_16x16x32_bf16 v[18:21], v[50:53], v[130:133], v[22:25]
	v_mfma_f32_16x16x32_bf16 v[162:165], v[54:57], v[142:145], v[18:21]
	v_mfma_f32_16x16x32_bf16 v[18:21], v[58:61], v[130:133], v[26:29]
	v_mfma_f32_16x16x32_bf16 v[146:149], v[50:53], v[114:117], v[186:189]
	v_mfma_f32_16x16x32_bf16 v[158:161], v[166:169], v[142:145], v[18:21]
	v_mfma_f32_16x16x32_bf16 v[18:21], v[50:53], v[174:177], v[30:33]
	v_mfma_f32_16x16x32_bf16 v[186:189], v[54:57], v[126:129], v[146:149]
	v_mfma_f32_16x16x32_bf16 v[146:149], v[54:57], v[190:193], v[18:21]
	v_mfma_f32_16x16x32_bf16 v[18:21], v[58:61], v[174:177], v[34:37]
	v_mfma_f32_16x16x32_bf16 v[142:145], v[166:169], v[190:193], v[18:21]
	v_mfma_f32_16x16x32_bf16 v[18:21], v[50:53], v[194:197], v[38:41]
	v_mfma_f32_16x16x32_bf16 v[130:133], v[54:57], v[218:221], v[18:21]
	v_mfma_f32_16x16x32_bf16 v[18:21], v[58:61], v[194:197], v[42:45]
	v_mfma_f32_16x16x32_bf16 v[126:129], v[166:169], v[218:221], v[18:21]
	s_mov_b32 m0, s72
	v_lshl_add_u64 v[114:115], v[228:229], 0, s[20:21]
	s_barrier
	s_nop 2
	ds_read_b128 v[18:21], v237 offset:49152
	ds_read_b128 v[22:25], v237 offset:50176
	ds_read_b128 v[26:29], v237 offset:51200
	ds_read_b128 v[30:33], v237 offset:52224
	ds_read_b128 v[34:37], v237 offset:53248
	ds_read_b128 v[38:41], v237 offset:54272
	ds_read_b128 v[42:45], v237 offset:55296
	ds_read_b128 v[174:177], v237 offset:56320
	global_load_lds_dwordx4 v[114:115], off
	s_mov_b32 m0, s22
	v_lshl_add_u64 v[114:115], v[230:231], 0, s[20:21]
	global_load_lds_dwordx4 v[114:115], off
	s_barrier
	s_waitcnt lgkmcnt(0)
	v_mfma_f32_16x16x32_bf16 v[114:117], v[70:73], v[18:21], v[122:125]
	v_mfma_f32_16x16x32_bf16 v[110:113], v[70:73], v[26:29], v[110:113]
	v_mfma_f32_16x16x32_bf16 v[94:97], v[70:73], v[34:37], v[94:97]
	v_mfma_f32_16x16x32_bf16 v[2:5], v[70:73], v[42:45], v[2:5]
	v_mfma_f32_16x16x32_bf16 v[122:125], v[78:81], v[22:25], v[114:117]
	v_mfma_f32_16x16x32_bf16 v[114:117], v[98:101], v[18:21], v[118:121]
	v_mfma_f32_16x16x32_bf16 v[110:113], v[78:81], v[30:33], v[110:113]
	v_mfma_f32_16x16x32_bf16 v[102:105], v[98:101], v[26:29], v[102:105]
	v_mfma_f32_16x16x32_bf16 v[94:97], v[78:81], v[38:41], v[94:97]
	v_mfma_f32_16x16x32_bf16 v[86:89], v[98:101], v[34:37], v[86:89]
	v_mfma_f32_16x16x32_bf16 v[78:81], v[78:81], v[174:177], v[2:5]
	v_mfma_f32_16x16x32_bf16 v[2:5], v[98:101], v[42:45], v[6:9]
	v_mfma_f32_16x16x32_bf16 v[118:121], v[106:109], v[22:25], v[114:117]
	v_mfma_f32_16x16x32_bf16 v[102:105], v[106:109], v[30:33], v[102:105]
	v_mfma_f32_16x16x32_bf16 v[86:89], v[106:109], v[38:41], v[86:89]
	v_mfma_f32_16x16x32_bf16 v[70:73], v[106:109], v[174:177], v[2:5]
	s_barrier
	s_add_i32 s8, s8, s53
	s_nop 0
	s_mov_b32 m0, s8
	v_lshl_add_u64 v[2:3], v[238:239], 0, s[20:21]
	global_load_lds_dwordx4 v[2:3], off
	s_add_i32 m0, s8, 0x2000
	v_lshl_add_u64 v[2:3], v[240:241], 0, s[20:21]
	global_load_lds_dwordx4 v[2:3], off
	s_waitcnt vmcnt(6)
	s_barrier
	v_mfma_f32_16x16x32_bf16 v[2:5], v[50:53], v[18:21], v[10:13]
	v_mfma_f32_16x16x32_bf16 v[114:117], v[54:57], v[22:25], v[2:5]
	v_mfma_f32_16x16x32_bf16 v[2:5], v[58:61], v[18:21], v[14:17]
	v_mfma_f32_16x16x32_bf16 v[106:109], v[166:169], v[22:25], v[2:5]
	v_mfma_f32_16x16x32_bf16 v[2:5], v[50:53], v[26:29], v[46:49]
	v_mfma_f32_16x16x32_bf16 v[98:101], v[54:57], v[30:33], v[2:5]
	v_mfma_f32_16x16x32_bf16 v[2:5], v[58:61], v[26:29], v[90:93]
	v_mfma_f32_16x16x32_bf16 v[90:93], v[166:169], v[30:33], v[2:5]
	v_mfma_f32_16x16x32_bf16 v[2:5], v[50:53], v[34:37], v[82:85]
	v_mfma_f32_16x16x32_bf16 v[82:85], v[54:57], v[38:41], v[2:5]
	v_mfma_f32_16x16x32_bf16 v[2:5], v[58:61], v[34:37], v[74:77]
	v_mfma_f32_16x16x32_bf16 v[74:77], v[166:169], v[38:41], v[2:5]
	v_mfma_f32_16x16x32_bf16 v[2:5], v[50:53], v[42:45], v[66:69]
	v_mfma_f32_16x16x32_bf16 v[66:69], v[54:57], v[174:177], v[2:5]
	v_mfma_f32_16x16x32_bf16 v[2:5], v[58:61], v[42:45], v[62:65]
	v_mfma_f32_16x16x32_bf16 v[62:65], v[166:169], v[174:177], v[2:5]
	s_add_u32 vcc_lo, vcc_lo, 0x100
	s_addc_u32 vcc_hi, vcc_hi, 0
	s_cmp_ge_u32 s63, s91
	s_mov_b64 s[10:11], s[6:7]
	s_mov_b32 s8, s63
	s_barrier
	s_cbranch_scc0 .LBB0_861

.LBB0_1009:
	v_lshlrev_b32_e32 v4, 1, v0
	v_mov_b32_e32 v5, v1
	v_lshl_add_u64 v[4:5], v[108:109], 0, v[4:5]
	s_add_i32 m0, s36, 0xc800
	s_and_b64 vcc, exec, s[4:5]
	global_load_lds_dwordx4 v[4:5], off
	v_lshlrev_b32_e32 v4, 1, v112
	v_mov_b32_e32 v5, v1
	s_add_i32 m0, s36, 0xe800
	v_lshl_add_u64 v[4:5], v[110:111], 0, v[4:5]
	global_load_lds_dwordx4 v[4:5], off
	v_lshlrev_b32_e32 v4, 1, v116
	v_mov_b32_e32 v5, v1
	s_add_i32 m0, s36, 0x10800
	v_lshl_add_u64 v[4:5], v[114:115], 0, v[4:5]
	global_load_lds_dwordx4 v[4:5], off
	s_cbranch_vccnz .LBB0_1012
	v_lshlrev_b32_e32 v4, 1, v120
	v_mov_b32_e32 v5, v1
	s_add_i32 m0, s36, 0x12800
	v_lshl_add_u64 v[4:5], v[118:119], 0, v[4:5]
	global_load_lds_dwordx4 v[4:5], off
	s_branch .LBB0_1012
.LBB0_1011:
	v_mov_b32_e32 v121, v1
	s_add_i32 m0, s36, 0xc400
	v_lshl_add_u64 v[4:5], v[118:119], 0, v[120:121]
	global_load_lds_dwordx4 v[4:5], off
	s_cmp_lt_i32 s37, 3
	s_cbranch_scc0 .LBB0_1009

.LBB0_1151:
	v_mov_b64_e32 v[2:3], 0x200
	s_ashr_i32 s13, s12, 31
	v_cmp_lt_i64_e32 vcc, s[14:15], v[2:3]
	s_lshl_b64 s[14:15], s[12:13], 19
	s_add_u32 s14, s80, s14
	s_addc_u32 s15, s83, s15
	s_and_b64 s[16:17], vcc, exec
	s_cselect_b32 s13, s15, s7
	s_cselect_b32 s54, s14, s6
	s_ashr_i32 s11, s10, 31
	s_lshl_b64 s[16:17], s[10:11], 19
	s_add_u32 s16, s23, s16
	s_addc_u32 s17, s36, s17
	s_and_b64 s[26:27], vcc, exec
	s_cselect_b32 s11, s17, s9
	s_cselect_b32 s55, s16, s8
	s_add_u32 s6, s6, 0x40080
	s_addc_u32 s7, s7, 0
	s_add_u32 s56, s8, 0x100
	s_addc_u32 s57, s9, 0
	s_mov_b32 s58, -2
	s_add_u32 s8, s6, 0xfffc0080
	s_addc_u32 s9, s7, -1
	s_add_i32 s59, 0, 0x10000
	v_add_u32_e32 v0, s59, v249
	ds_read_b128 v[2:5], v0
	ds_read_b128 v[6:9], v0 offset:1024
	ds_read_b128 v[10:13], v0 offset:2048
	ds_read_b128 v[14:17], v0 offset:3072
	s_cmp_eq_u32 s58, 12
	s_cselect_b32 s27, s13, s9
	s_cselect_b32 s26, s54, s8
	s_cselect_b32 s9, s11, s57
	s_cselect_b32 s8, s55, s56
	v_lshl_add_u64 v[50:51], s[6:7], 0, v[234:235]
	s_add_i32 m0, s38, 0xc000
	ds_read_b128 v[18:21], v222
	ds_read_b128 v[22:25], v222 offset:1024
	ds_read_b128 v[26:29], v222 offset:2048
	ds_read_b128 v[30:33], v222 offset:3072
	ds_read_b128 v[34:37], v222 offset:4096
	ds_read_b128 v[38:41], v222 offset:5120
	ds_read_b128 v[42:45], v222 offset:6144
	ds_read_b128 v[46:49], v222 offset:7168
	global_load_lds_dwordx4 v[50:51], off
	s_add_i32 m0, s38, 0xe000
	v_lshl_add_u64 v[50:51], s[6:7], 0, v[236:237]
	global_load_lds_dwordx4 v[50:51], off
	s_waitcnt lgkmcnt(8)
	s_barrier
	s_waitcnt lgkmcnt(0)
	v_mfma_f32_16x16x32_bf16 v[150:153], v[10:13], v[42:45], 0
	v_mfma_f32_16x16x32_bf16 v[50:53], v[2:5], v[18:21], 0
	v_mfma_f32_16x16x32_bf16 v[54:57], v[10:13], v[18:21], 0
	v_mfma_f32_16x16x32_bf16 v[58:61], v[2:5], v[26:29], 0
	v_mfma_f32_16x16x32_bf16 v[62:65], v[10:13], v[26:29], 0
	v_mfma_f32_16x16x32_bf16 v[66:69], v[2:5], v[34:37], 0
	v_mfma_f32_16x16x32_bf16 v[70:73], v[10:13], v[34:37], 0
	v_mfma_f32_16x16x32_bf16 v[74:77], v[2:5], v[42:45], 0
	v_mfma_f32_16x16x32_bf16 v[150:153], v[14:17], v[46:49], v[150:153]
	v_mfma_f32_16x16x32_bf16 v[50:53], v[6:9], v[22:25], v[50:53]
	v_mfma_f32_16x16x32_bf16 v[54:57], v[14:17], v[22:25], v[54:57]
	v_mfma_f32_16x16x32_bf16 v[58:61], v[6:9], v[30:33], v[58:61]
	v_mfma_f32_16x16x32_bf16 v[62:65], v[14:17], v[30:33], v[62:65]
	v_mfma_f32_16x16x32_bf16 v[66:69], v[6:9], v[38:41], v[66:69]
	v_mfma_f32_16x16x32_bf16 v[70:73], v[14:17], v[38:41], v[70:73]
	v_mfma_f32_16x16x32_bf16 v[74:77], v[6:9], v[46:49], v[74:77]
	s_barrier
	s_add_i32 s64, 0, 0x14000
	s_add_i32 s59, s59, s37
	v_add_u32_e32 v0, s64, v249
	v_lshl_add_u64 v[238:239], s[8:9], 0, v[230:231]
	s_mov_b32 m0, s59
	ds_read_b128 v[154:157], v0
	ds_read_b128 v[166:169], v0 offset:1024
	ds_read_b128 v[170:173], v0 offset:2048
	ds_read_b128 v[182:185], v0 offset:3072
	global_load_lds_dwordx4 v[238:239], off
	s_add_i32 m0, s59, 0x2000
	v_lshl_add_u64 v[240:241], s[8:9], 0, v[226:227]
	global_load_lds_dwordx4 v[240:241], off
	s_barrier
	s_waitcnt lgkmcnt(0)
	v_mfma_f32_16x16x32_bf16 v[186:189], v[154:157], v[18:21], 0
	v_mfma_f32_16x16x32_bf16 v[18:21], v[170:173], v[18:21], 0
	v_mfma_f32_16x16x32_bf16 v[194:197], v[166:169], v[22:25], v[186:189]
	v_mfma_f32_16x16x32_bf16 v[18:21], v[182:185], v[22:25], v[18:21]
	v_mfma_f32_16x16x32_bf16 v[22:25], v[154:157], v[26:29], 0
	v_mfma_f32_16x16x32_bf16 v[26:29], v[170:173], v[26:29], 0
	v_mfma_f32_16x16x32_bf16 v[22:25], v[166:169], v[30:33], v[22:25]
	v_mfma_f32_16x16x32_bf16 v[26:29], v[182:185], v[30:33], v[26:29]
	v_mfma_f32_16x16x32_bf16 v[30:33], v[154:157], v[34:37], 0
	v_mfma_f32_16x16x32_bf16 v[34:37], v[170:173], v[34:37], 0
	v_mfma_f32_16x16x32_bf16 v[30:33], v[166:169], v[38:41], v[30:33]
	v_mfma_f32_16x16x32_bf16 v[34:37], v[182:185], v[38:41], v[34:37]
	v_mfma_f32_16x16x32_bf16 v[38:41], v[154:157], v[42:45], 0
	v_mfma_f32_16x16x32_bf16 v[42:45], v[170:173], v[42:45], 0
	v_mfma_f32_16x16x32_bf16 v[38:41], v[166:169], v[46:49], v[38:41]
	v_mfma_f32_16x16x32_bf16 v[42:45], v[182:185], v[46:49], v[42:45]
	s_mov_b32 m0, s38
	v_lshl_add_u64 v[242:243], s[26:27], 0, v[232:233]
	s_barrier
	ds_read_b128 v[46:49], v222 offset:16384
	ds_read_b128 v[142:145], v222 offset:17408
	ds_read_b128 v[146:149], v222 offset:18432
	ds_read_b128 v[158:161], v222 offset:19456
	ds_read_b128 v[162:165], v222 offset:20480
	ds_read_b128 v[174:177], v222 offset:21504
	ds_read_b128 v[178:181], v222 offset:22528
	ds_read_b128 v[186:189], v222 offset:23552
	global_load_lds_dwordx4 v[242:243], off
	s_mov_b32 m0, s39
	v_lshl_add_u64 v[224:225], s[26:27], 0, v[228:229]
	global_load_lds_dwordx4 v[224:225], off
	s_barrier
	s_waitcnt lgkmcnt(0)
	v_mfma_f32_16x16x32_bf16 v[138:141], v[2:5], v[46:49], 0
	v_mfma_f32_16x16x32_bf16 v[134:137], v[10:13], v[46:49], 0
	v_mfma_f32_16x16x32_bf16 v[122:125], v[2:5], v[146:149], 0
	v_mfma_f32_16x16x32_bf16 v[118:121], v[10:13], v[146:149], 0
	v_mfma_f32_16x16x32_bf16 v[106:109], v[2:5], v[162:165], 0
	v_mfma_f32_16x16x32_bf16 v[102:105], v[10:13], v[162:165], 0
	v_mfma_f32_16x16x32_bf16 v[2:5], v[2:5], v[178:181], 0
	v_mfma_f32_16x16x32_bf16 v[138:141], v[6:9], v[142:145], v[138:141]
	v_mfma_f32_16x16x32_bf16 v[134:137], v[14:17], v[142:145], v[134:137]
	v_mfma_f32_16x16x32_bf16 v[122:125], v[6:9], v[158:161], v[122:125]
	v_mfma_f32_16x16x32_bf16 v[118:121], v[14:17], v[158:161], v[118:121]
	v_mfma_f32_16x16x32_bf16 v[106:109], v[6:9], v[174:177], v[106:109]
	v_mfma_f32_16x16x32_bf16 v[102:105], v[14:17], v[174:177], v[102:105]
	v_mfma_f32_16x16x32_bf16 v[2:5], v[6:9], v[186:189], v[2:5]
	v_mfma_f32_16x16x32_bf16 v[6:9], v[10:13], v[178:181], 0
	v_mfma_f32_16x16x32_bf16 v[6:9], v[14:17], v[186:189], v[6:9]
	s_barrier
	s_add_u32 s62, s8, 0x40000
	s_addc_u32 s63, s9, 0
	s_add_i32 s59, s64, s37
	s_mov_b32 m0, s59
	v_lshl_add_u64 v[10:11], s[62:63], 0, v[230:231]
	global_load_lds_dwordx4 v[10:11], off
	s_add_i32 m0, s59, 0x2000
	v_lshl_add_u64 v[10:11], s[62:63], 0, v[226:227]
	global_load_lds_dwordx4 v[10:11], off
	s_waitcnt vmcnt(6)
	s_barrier
	v_mfma_f32_16x16x32_bf16 v[86:89], v[170:173], v[146:149], 0
	v_mfma_f32_16x16x32_bf16 v[110:113], v[182:185], v[158:161], v[86:89]
	v_mfma_f32_16x16x32_bf16 v[86:89], v[154:157], v[162:165], 0
	v_mfma_f32_16x16x32_bf16 v[98:101], v[166:169], v[174:177], v[86:89]
	v_mfma_f32_16x16x32_bf16 v[86:89], v[170:173], v[162:165], 0
	v_mfma_f32_16x16x32_bf16 v[82:85], v[154:157], v[178:181], 0
	v_mfma_f32_16x16x32_bf16 v[78:81], v[170:173], v[178:181], 0
	v_mfma_f32_16x16x32_bf16 v[10:13], v[154:157], v[46:49], 0
	v_mfma_f32_16x16x32_bf16 v[14:17], v[170:173], v[46:49], 0
	v_mfma_f32_16x16x32_bf16 v[46:49], v[154:157], v[146:149], 0
	v_mfma_f32_16x16x32_bf16 v[94:97], v[182:185], v[174:177], v[86:89]
	v_mfma_f32_16x16x32_bf16 v[82:85], v[166:169], v[186:189], v[82:85]
	v_mfma_f32_16x16x32_bf16 v[78:81], v[182:185], v[186:189], v[78:81]
	v_mfma_f32_16x16x32_bf16 v[10:13], v[166:169], v[142:145], v[10:13]
	v_mfma_f32_16x16x32_bf16 v[14:17], v[182:185], v[142:145], v[14:17]
	v_mfma_f32_16x16x32_bf16 v[46:49], v[166:169], v[158:161], v[46:49]
	s_add_i32 s59, 0, 0x18000
	v_add_u32_e32 v0, s59, v249
	s_barrier
	ds_read_b128 v[86:89], v0
	ds_read_b128 v[90:93], v0 offset:1024
	ds_read_b128 v[114:117], v0 offset:2048
	ds_read_b128 v[126:129], v0 offset:3072
	s_add_u32 s26, s26, 0x40000
	s_addc_u32 s27, s27, 0
	s_mov_b32 m0, s40
	v_lshl_add_u64 v[154:155], s[26:27], 0, v[232:233]
	ds_read_b128 v[130:133], v222 offset:32768
	ds_read_b128 v[142:145], v222 offset:33792
	ds_read_b128 v[146:149], v222 offset:34816
	ds_read_b128 v[158:161], v222 offset:35840
	ds_read_b128 v[206:209], v222 offset:36864
	ds_read_b128 v[210:213], v222 offset:37888
	ds_read_b128 v[214:217], v222 offset:38912
	ds_read_b128 v[218:221], v222 offset:39936
	global_load_lds_dwordx4 v[154:155], off
	s_mov_b32 m0, s41
	v_lshl_add_u64 v[154:155], s[26:27], 0, v[228:229]
	global_load_lds_dwordx4 v[154:155], off
	s_waitcnt lgkmcnt(8)
	s_barrier
	s_waitcnt lgkmcnt(0)
	v_mfma_f32_16x16x32_bf16 v[50:53], v[86:89], v[130:133], v[50:53]
	v_mfma_f32_16x16x32_bf16 v[202:205], v[90:93], v[142:145], v[50:53]
	v_mfma_f32_16x16x32_bf16 v[50:53], v[114:117], v[130:133], v[54:57]
	v_mfma_f32_16x16x32_bf16 v[198:201], v[126:129], v[142:145], v[50:53]
	v_mfma_f32_16x16x32_bf16 v[50:53], v[86:89], v[146:149], v[58:61]
	v_mfma_f32_16x16x32_bf16 v[186:189], v[90:93], v[158:161], v[50:53]
	v_mfma_f32_16x16x32_bf16 v[50:53], v[114:117], v[146:149], v[62:65]
	v_mfma_f32_16x16x32_bf16 v[182:185], v[126:129], v[158:161], v[50:53]
	v_mfma_f32_16x16x32_bf16 v[50:53], v[86:89], v[206:209], v[66:69]
	v_mfma_f32_16x16x32_bf16 v[170:173], v[90:93], v[210:213], v[50:53]
	v_mfma_f32_16x16x32_bf16 v[50:53], v[114:117], v[206:209], v[70:73]
	v_mfma_f32_16x16x32_bf16 v[166:169], v[126:129], v[210:213], v[50:53]
	v_mfma_f32_16x16x32_bf16 v[50:53], v[86:89], v[214:217], v[74:77]
	v_mfma_f32_16x16x32_bf16 v[154:157], v[90:93], v[218:221], v[50:53]
	v_mfma_f32_16x16x32_bf16 v[50:53], v[114:117], v[214:217], v[150:153]
	v_mfma_f32_16x16x32_bf16 v[150:153], v[126:129], v[218:221], v[50:53]
	s_barrier
	s_add_i32 s26, 0, 0x1c000
	s_add_i32 s27, s59, s37
	v_add_u32_e32 v0, s26, v249
	v_lshl_add_u64 v[66:67], v[238:239], 0, s[20:21]
	s_mov_b32 m0, s27
	ds_read_b128 v[50:53], v0
	ds_read_b128 v[54:57], v0 offset:1024
	ds_read_b128 v[58:61], v0 offset:2048
	ds_read_b128 v[62:65], v0 offset:3072
	global_load_lds_dwordx4 v[66:67], off
	s_add_i32 m0, s27, 0x2000
	v_lshl_add_u64 v[66:67], v[240:241], 0, s[20:21]
	global_load_lds_dwordx4 v[66:67], off
	s_barrier
	s_waitcnt lgkmcnt(0)
	v_mfma_f32_16x16x32_bf16 v[18:21], v[58:61], v[130:133], v[18:21]
	v_mfma_f32_16x16x32_bf16 v[190:193], v[62:65], v[142:145], v[18:21]
	v_mfma_f32_16x16x32_bf16 v[18:21], v[50:53], v[146:149], v[22:25]
	v_mfma_f32_16x16x32_bf16 v[178:181], v[54:57], v[158:161], v[18:21]
	v_mfma_f32_16x16x32_bf16 v[18:21], v[58:61], v[146:149], v[26:29]
	v_mfma_f32_16x16x32_bf16 v[174:177], v[62:65], v[158:161], v[18:21]
	v_mfma_f32_16x16x32_bf16 v[18:21], v[50:53], v[206:209], v[30:33]
	v_mfma_f32_16x16x32_bf16 v[162:165], v[54:57], v[210:213], v[18:21]
	v_mfma_f32_16x16x32_bf16 v[18:21], v[58:61], v[206:209], v[34:37]
	v_mfma_f32_16x16x32_bf16 v[158:161], v[62:65], v[210:213], v[18:21]
	v_mfma_f32_16x16x32_bf16 v[18:21], v[50:53], v[214:217], v[38:41]
	v_mfma_f32_16x16x32_bf16 v[66:69], v[50:53], v[130:133], v[194:197]
	v_mfma_f32_16x16x32_bf16 v[146:149], v[54:57], v[218:221], v[18:21]
	v_mfma_f32_16x16x32_bf16 v[18:21], v[58:61], v[214:217], v[42:45]
	v_mfma_f32_16x16x32_bf16 v[194:197], v[54:57], v[142:145], v[66:69]
	v_mfma_f32_16x16x32_bf16 v[142:145], v[62:65], v[218:221], v[18:21]
	s_mov_b32 m0, s44
	v_lshl_add_u64 v[70:71], v[242:243], 0, s[20:21]
	s_barrier
	s_nop 1
	ds_read_b128 v[18:21], v222 offset:49152
	ds_read_b128 v[22:25], v222 offset:50176
	ds_read_b128 v[26:29], v222 offset:51200
	ds_read_b128 v[30:33], v222 offset:52224
	ds_read_b128 v[34:37], v222 offset:53248
	ds_read_b128 v[38:41], v222 offset:54272
	ds_read_b128 v[42:45], v222 offset:55296
	ds_read_b128 v[66:69], v222 offset:56320
	global_load_lds_dwordx4 v[70:71], off
	s_mov_b32 m0, s45
	v_lshl_add_u64 v[70:71], v[224:225], 0, s[20:21]
	global_load_lds_dwordx4 v[70:71], off
	s_barrier
	s_waitcnt lgkmcnt(0)
	v_mfma_f32_16x16x32_bf16 v[70:73], v[86:89], v[18:21], v[138:141]
	v_mfma_f32_16x16x32_bf16 v[138:141], v[90:93], v[22:25], v[70:73]
	v_mfma_f32_16x16x32_bf16 v[70:73], v[114:117], v[18:21], v[134:137]
	v_mfma_f32_16x16x32_bf16 v[134:137], v[126:129], v[22:25], v[70:73]
	v_mfma_f32_16x16x32_bf16 v[70:73], v[86:89], v[26:29], v[122:125]
	v_mfma_f32_16x16x32_bf16 v[122:125], v[90:93], v[30:33], v[70:73]
	v_mfma_f32_16x16x32_bf16 v[70:73], v[114:117], v[26:29], v[118:121]
	v_mfma_f32_16x16x32_bf16 v[118:121], v[126:129], v[30:33], v[70:73]
	v_mfma_f32_16x16x32_bf16 v[70:73], v[86:89], v[34:37], v[106:109]
	v_mfma_f32_16x16x32_bf16 v[2:5], v[86:89], v[42:45], v[2:5]
	v_mfma_f32_16x16x32_bf16 v[106:109], v[90:93], v[38:41], v[70:73]
	v_mfma_f32_16x16x32_bf16 v[70:73], v[114:117], v[34:37], v[102:105]
	v_mfma_f32_16x16x32_bf16 v[90:93], v[90:93], v[66:69], v[2:5]
	v_mfma_f32_16x16x32_bf16 v[2:5], v[114:117], v[42:45], v[6:9]
	v_mfma_f32_16x16x32_bf16 v[102:105], v[126:129], v[38:41], v[70:73]
	v_mfma_f32_16x16x32_bf16 v[86:89], v[126:129], v[66:69], v[2:5]
	s_barrier
	s_add_u32 s8, s8, 0x40080
	s_addc_u32 s9, s9, 0
	s_add_i32 s26, s26, s37
	s_nop 0
	s_mov_b32 m0, s26
	v_lshl_add_u64 v[2:3], s[8:9], 0, v[230:231]
	global_load_lds_dwordx4 v[2:3], off
	s_add_i32 m0, s26, 0x2000
	v_lshl_add_u64 v[2:3], s[8:9], 0, v[226:227]
	global_load_lds_dwordx4 v[2:3], off
	s_waitcnt vmcnt(6)
	s_barrier
	v_mfma_f32_16x16x32_bf16 v[2:5], v[50:53], v[18:21], v[10:13]
	v_mfma_f32_16x16x32_bf16 v[130:133], v[54:57], v[22:25], v[2:5]
	v_mfma_f32_16x16x32_bf16 v[2:5], v[58:61], v[18:21], v[14:17]
	v_mfma_f32_16x16x32_bf16 v[126:129], v[62:65], v[22:25], v[2:5]
	v_mfma_f32_16x16x32_bf16 v[2:5], v[50:53], v[26:29], v[46:49]
	v_mfma_f32_16x16x32_bf16 v[114:117], v[54:57], v[30:33], v[2:5]
	v_mfma_f32_16x16x32_bf16 v[2:5], v[58:61], v[26:29], v[110:113]
	v_mfma_f32_16x16x32_bf16 v[110:113], v[62:65], v[30:33], v[2:5]
	v_mfma_f32_16x16x32_bf16 v[2:5], v[50:53], v[34:37], v[98:101]
	v_mfma_f32_16x16x32_bf16 v[98:101], v[54:57], v[38:41], v[2:5]
	v_mfma_f32_16x16x32_bf16 v[2:5], v[58:61], v[34:37], v[94:97]
	v_mfma_f32_16x16x32_bf16 v[94:97], v[62:65], v[38:41], v[2:5]
	v_mfma_f32_16x16x32_bf16 v[2:5], v[50:53], v[42:45], v[82:85]
	v_mfma_f32_16x16x32_bf16 v[82:85], v[54:57], v[66:69], v[2:5]
	v_mfma_f32_16x16x32_bf16 v[2:5], v[58:61], v[42:45], v[78:81]
	v_mfma_f32_16x16x32_bf16 v[78:81], v[62:65], v[66:69], v[2:5]
	s_add_i32 s58, s58, 2
	s_add_u32 s6, s6, 0x100
	s_addc_u32 s7, s7, 0
	s_add_u32 s56, s56, 0x100
	s_addc_u32 s57, s57, 0
	s_cmp_gt_u32 s58, 13
	s_barrier
	s_cbranch_scc0 .LBB0_1152
	s_branch .Lpeel_exit_g3
.LBB0_1152:
	s_add_u32 s8, s6, 0xfffc0080
	s_addc_u32 s9, s7, -1
	s_add_i32 s59, 0, 0x10000
	v_add_u32_e32 v0, s59, v249
	ds_read_b128 v[2:5], v0
	ds_read_b128 v[6:9], v0 offset:1024
	ds_read_b128 v[10:13], v0 offset:2048
	ds_read_b128 v[14:17], v0 offset:3072
	s_cmp_eq_u32 s58, 12
	s_cselect_b32 s27, s13, s9
	s_cselect_b32 s26, s54, s8
	s_cselect_b32 s9, s11, s57
	s_cselect_b32 s8, s55, s56
	v_lshl_add_u64 v[50:51], s[6:7], 0, v[234:235]
	s_add_i32 m0, s38, 0xc000
	ds_read_b128 v[18:21], v222
	ds_read_b128 v[22:25], v222 offset:1024
	ds_read_b128 v[26:29], v222 offset:2048
	ds_read_b128 v[30:33], v222 offset:3072
	ds_read_b128 v[34:37], v222 offset:4096
	ds_read_b128 v[38:41], v222 offset:5120
	ds_read_b128 v[42:45], v222 offset:6144
	ds_read_b128 v[46:49], v222 offset:7168
	global_load_lds_dwordx4 v[50:51], off
	s_add_i32 m0, s38, 0xe000
	v_lshl_add_u64 v[50:51], s[6:7], 0, v[236:237]
	global_load_lds_dwordx4 v[50:51], off
	s_waitcnt lgkmcnt(8)
	s_barrier
	s_waitcnt lgkmcnt(0)
	v_mfma_f32_16x16x32_bf16 v[150:153], v[10:13], v[42:45], v[150:153]
	v_mfma_f32_16x16x32_bf16 v[50:53], v[2:5], v[18:21], v[202:205]
	v_mfma_f32_16x16x32_bf16 v[54:57], v[10:13], v[18:21], v[198:201]
	v_mfma_f32_16x16x32_bf16 v[58:61], v[2:5], v[26:29], v[186:189]
	v_mfma_f32_16x16x32_bf16 v[62:65], v[10:13], v[26:29], v[182:185]
	v_mfma_f32_16x16x32_bf16 v[66:69], v[2:5], v[34:37], v[170:173]
	v_mfma_f32_16x16x32_bf16 v[70:73], v[10:13], v[34:37], v[166:169]
	v_mfma_f32_16x16x32_bf16 v[74:77], v[2:5], v[42:45], v[154:157]
	v_mfma_f32_16x16x32_bf16 v[150:153], v[14:17], v[46:49], v[150:153]
	v_mfma_f32_16x16x32_bf16 v[50:53], v[6:9], v[22:25], v[50:53]
	v_mfma_f32_16x16x32_bf16 v[54:57], v[14:17], v[22:25], v[54:57]
	v_mfma_f32_16x16x32_bf16 v[58:61], v[6:9], v[30:33], v[58:61]
	v_mfma_f32_16x16x32_bf16 v[62:65], v[14:17], v[30:33], v[62:65]
	v_mfma_f32_16x16x32_bf16 v[66:69], v[6:9], v[38:41], v[66:69]
	v_mfma_f32_16x16x32_bf16 v[70:73], v[14:17], v[38:41], v[70:73]
	v_mfma_f32_16x16x32_bf16 v[74:77], v[6:9], v[46:49], v[74:77]
	s_barrier
	s_add_i32 s64, 0, 0x14000
	s_add_i32 s59, s59, s37
	v_add_u32_e32 v0, s64, v249
	v_lshl_add_u64 v[238:239], s[8:9], 0, v[230:231]
	s_mov_b32 m0, s59
	ds_read_b128 v[154:157], v0
	ds_read_b128 v[166:169], v0 offset:1024
	ds_read_b128 v[170:173], v0 offset:2048
	ds_read_b128 v[182:185], v0 offset:3072
	global_load_lds_dwordx4 v[238:239], off
	s_add_i32 m0, s59, 0x2000
	v_lshl_add_u64 v[240:241], s[8:9], 0, v[226:227]
	global_load_lds_dwordx4 v[240:241], off
	s_barrier
	s_waitcnt lgkmcnt(0)
	v_mfma_f32_16x16x32_bf16 v[186:189], v[154:157], v[18:21], v[194:197]
	v_mfma_f32_16x16x32_bf16 v[18:21], v[170:173], v[18:21], v[190:193]
	v_mfma_f32_16x16x32_bf16 v[194:197], v[166:169], v[22:25], v[186:189]
	v_mfma_f32_16x16x32_bf16 v[18:21], v[182:185], v[22:25], v[18:21]
	v_mfma_f32_16x16x32_bf16 v[22:25], v[154:157], v[26:29], v[178:181]
	v_mfma_f32_16x16x32_bf16 v[26:29], v[170:173], v[26:29], v[174:177]
	v_mfma_f32_16x16x32_bf16 v[22:25], v[166:169], v[30:33], v[22:25]
	v_mfma_f32_16x16x32_bf16 v[26:29], v[182:185], v[30:33], v[26:29]
	v_mfma_f32_16x16x32_bf16 v[30:33], v[154:157], v[34:37], v[162:165]
	v_mfma_f32_16x16x32_bf16 v[34:37], v[170:173], v[34:37], v[158:161]
	v_mfma_f32_16x16x32_bf16 v[30:33], v[166:169], v[38:41], v[30:33]
	v_mfma_f32_16x16x32_bf16 v[34:37], v[182:185], v[38:41], v[34:37]
	v_mfma_f32_16x16x32_bf16 v[38:41], v[154:157], v[42:45], v[146:149]
	v_mfma_f32_16x16x32_bf16 v[42:45], v[170:173], v[42:45], v[142:145]
	v_mfma_f32_16x16x32_bf16 v[38:41], v[166:169], v[46:49], v[38:41]
	v_mfma_f32_16x16x32_bf16 v[42:45], v[182:185], v[46:49], v[42:45]
	s_mov_b32 m0, s38
	v_lshl_add_u64 v[242:243], s[26:27], 0, v[232:233]
	s_barrier
	ds_read_b128 v[46:49], v222 offset:16384
	ds_read_b128 v[142:145], v222 offset:17408
	ds_read_b128 v[146:149], v222 offset:18432
	ds_read_b128 v[158:161], v222 offset:19456
	ds_read_b128 v[162:165], v222 offset:20480
	ds_read_b128 v[174:177], v222 offset:21504
	ds_read_b128 v[178:181], v222 offset:22528
	ds_read_b128 v[186:189], v222 offset:23552
	global_load_lds_dwordx4 v[242:243], off
	s_mov_b32 m0, s39
	v_lshl_add_u64 v[224:225], s[26:27], 0, v[228:229]
	global_load_lds_dwordx4 v[224:225], off
	s_barrier
	s_waitcnt lgkmcnt(0)
	v_mfma_f32_16x16x32_bf16 v[138:141], v[2:5], v[46:49], v[138:141]
	v_mfma_f32_16x16x32_bf16 v[134:137], v[10:13], v[46:49], v[134:137]
	v_mfma_f32_16x16x32_bf16 v[122:125], v[2:5], v[146:149], v[122:125]
	v_mfma_f32_16x16x32_bf16 v[118:121], v[10:13], v[146:149], v[118:121]
	v_mfma_f32_16x16x32_bf16 v[106:109], v[2:5], v[162:165], v[106:109]
	v_mfma_f32_16x16x32_bf16 v[102:105], v[10:13], v[162:165], v[102:105]
	v_mfma_f32_16x16x32_bf16 v[2:5], v[2:5], v[178:181], v[90:93]
	v_mfma_f32_16x16x32_bf16 v[138:141], v[6:9], v[142:145], v[138:141]
	v_mfma_f32_16x16x32_bf16 v[134:137], v[14:17], v[142:145], v[134:137]
	v_mfma_f32_16x16x32_bf16 v[122:125], v[6:9], v[158:161], v[122:125]
	v_mfma_f32_16x16x32_bf16 v[118:121], v[14:17], v[158:161], v[118:121]
	v_mfma_f32_16x16x32_bf16 v[106:109], v[6:9], v[174:177], v[106:109]
	v_mfma_f32_16x16x32_bf16 v[102:105], v[14:17], v[174:177], v[102:105]
	v_mfma_f32_16x16x32_bf16 v[2:5], v[6:9], v[186:189], v[2:5]
	v_mfma_f32_16x16x32_bf16 v[6:9], v[10:13], v[178:181], v[86:89]
	v_mfma_f32_16x16x32_bf16 v[6:9], v[14:17], v[186:189], v[6:9]
	s_barrier
	s_add_u32 s62, s8, 0x40000
	s_addc_u32 s63, s9, 0
	s_add_i32 s59, s64, s37
	s_mov_b32 m0, s59
	v_lshl_add_u64 v[10:11], s[62:63], 0, v[230:231]
	global_load_lds_dwordx4 v[10:11], off
	s_add_i32 m0, s59, 0x2000
	v_lshl_add_u64 v[10:11], s[62:63], 0, v[226:227]
	global_load_lds_dwordx4 v[10:11], off
	s_waitcnt vmcnt(6)
	s_barrier
	v_mfma_f32_16x16x32_bf16 v[86:89], v[170:173], v[146:149], v[110:113]
	v_mfma_f32_16x16x32_bf16 v[110:113], v[182:185], v[158:161], v[86:89]
	v_mfma_f32_16x16x32_bf16 v[86:89], v[154:157], v[162:165], v[98:101]
	v_mfma_f32_16x16x32_bf16 v[98:101], v[166:169], v[174:177], v[86:89]
	v_mfma_f32_16x16x32_bf16 v[86:89], v[170:173], v[162:165], v[94:97]
	v_mfma_f32_16x16x32_bf16 v[82:85], v[154:157], v[178:181], v[82:85]
	v_mfma_f32_16x16x32_bf16 v[78:81], v[170:173], v[178:181], v[78:81]
	v_mfma_f32_16x16x32_bf16 v[10:13], v[154:157], v[46:49], v[130:133]
	v_mfma_f32_16x16x32_bf16 v[14:17], v[170:173], v[46:49], v[126:129]
	v_mfma_f32_16x16x32_bf16 v[46:49], v[154:157], v[146:149], v[114:117]
	v_mfma_f32_16x16x32_bf16 v[94:97], v[182:185], v[174:177], v[86:89]
	v_mfma_f32_16x16x32_bf16 v[82:85], v[166:169], v[186:189], v[82:85]
	v_mfma_f32_16x16x32_bf16 v[78:81], v[182:185], v[186:189], v[78:81]
	v_mfma_f32_16x16x32_bf16 v[10:13], v[166:169], v[142:145], v[10:13]
	v_mfma_f32_16x16x32_bf16 v[14:17], v[182:185], v[142:145], v[14:17]
	v_mfma_f32_16x16x32_bf16 v[46:49], v[166:169], v[158:161], v[46:49]
	s_add_i32 s59, 0, 0x18000
	v_add_u32_e32 v0, s59, v249
	s_barrier
	ds_read_b128 v[86:89], v0
	ds_read_b128 v[90:93], v0 offset:1024
	ds_read_b128 v[114:117], v0 offset:2048
	ds_read_b128 v[126:129], v0 offset:3072
	s_add_u32 s26, s26, 0x40000
	s_addc_u32 s27, s27, 0
	s_mov_b32 m0, s40
	v_lshl_add_u64 v[154:155], s[26:27], 0, v[232:233]
	ds_read_b128 v[130:133], v222 offset:32768
	ds_read_b128 v[142:145], v222 offset:33792
	ds_read_b128 v[146:149], v222 offset:34816
	ds_read_b128 v[158:161], v222 offset:35840
	ds_read_b128 v[206:209], v222 offset:36864
	ds_read_b128 v[210:213], v222 offset:37888
	ds_read_b128 v[214:217], v222 offset:38912
	ds_read_b128 v[218:221], v222 offset:39936
	global_load_lds_dwordx4 v[154:155], off
	s_mov_b32 m0, s41
	v_lshl_add_u64 v[154:155], s[26:27], 0, v[228:229]
	global_load_lds_dwordx4 v[154:155], off
	s_waitcnt lgkmcnt(8)
	s_barrier
	s_waitcnt lgkmcnt(0)
	v_mfma_f32_16x16x32_bf16 v[50:53], v[86:89], v[130:133], v[50:53]
	v_mfma_f32_16x16x32_bf16 v[202:205], v[90:93], v[142:145], v[50:53]
	v_mfma_f32_16x16x32_bf16 v[50:53], v[114:117], v[130:133], v[54:57]
	v_mfma_f32_16x16x32_bf16 v[198:201], v[126:129], v[142:145], v[50:53]
	v_mfma_f32_16x16x32_bf16 v[50:53], v[86:89], v[146:149], v[58:61]
	v_mfma_f32_16x16x32_bf16 v[186:189], v[90:93], v[158:161], v[50:53]
	v_mfma_f32_16x16x32_bf16 v[50:53], v[114:117], v[146:149], v[62:65]
	v_mfma_f32_16x16x32_bf16 v[182:185], v[126:129], v[158:161], v[50:53]
	v_mfma_f32_16x16x32_bf16 v[50:53], v[86:89], v[206:209], v[66:69]
	v_mfma_f32_16x16x32_bf16 v[170:173], v[90:93], v[210:213], v[50:53]
	v_mfma_f32_16x16x32_bf16 v[50:53], v[114:117], v[206:209], v[70:73]
	v_mfma_f32_16x16x32_bf16 v[166:169], v[126:129], v[210:213], v[50:53]
	v_mfma_f32_16x16x32_bf16 v[50:53], v[86:89], v[214:217], v[74:77]
	v_mfma_f32_16x16x32_bf16 v[154:157], v[90:93], v[218:221], v[50:53]
	v_mfma_f32_16x16x32_bf16 v[50:53], v[114:117], v[214:217], v[150:153]
	v_mfma_f32_16x16x32_bf16 v[150:153], v[126:129], v[218:221], v[50:53]
	s_barrier
	s_add_i32 s26, 0, 0x1c000
	s_add_i32 s27, s59, s37
	v_add_u32_e32 v0, s26, v249
	v_lshl_add_u64 v[66:67], v[238:239], 0, s[20:21]
	s_mov_b32 m0, s27
	ds_read_b128 v[50:53], v0
	ds_read_b128 v[54:57], v0 offset:1024
	ds_read_b128 v[58:61], v0 offset:2048
	ds_read_b128 v[62:65], v0 offset:3072
	global_load_lds_dwordx4 v[66:67], off
	s_add_i32 m0, s27, 0x2000
	v_lshl_add_u64 v[66:67], v[240:241], 0, s[20:21]
	global_load_lds_dwordx4 v[66:67], off
	s_barrier
	s_waitcnt lgkmcnt(0)
	v_mfma_f32_16x16x32_bf16 v[18:21], v[58:61], v[130:133], v[18:21]
	v_mfma_f32_16x16x32_bf16 v[190:193], v[62:65], v[142:145], v[18:21]
	v_mfma_f32_16x16x32_bf16 v[18:21], v[50:53], v[146:149], v[22:25]
	v_mfma_f32_16x16x32_bf16 v[178:181], v[54:57], v[158:161], v[18:21]
	v_mfma_f32_16x16x32_bf16 v[18:21], v[58:61], v[146:149], v[26:29]
	v_mfma_f32_16x16x32_bf16 v[174:177], v[62:65], v[158:161], v[18:21]
	v_mfma_f32_16x16x32_bf16 v[18:21], v[50:53], v[206:209], v[30:33]
	v_mfma_f32_16x16x32_bf16 v[162:165], v[54:57], v[210:213], v[18:21]
	v_mfma_f32_16x16x32_bf16 v[18:21], v[58:61], v[206:209], v[34:37]
	v_mfma_f32_16x16x32_bf16 v[158:161], v[62:65], v[210:213], v[18:21]
	v_mfma_f32_16x16x32_bf16 v[18:21], v[50:53], v[214:217], v[38:41]
	v_mfma_f32_16x16x32_bf16 v[66:69], v[50:53], v[130:133], v[194:197]
	v_mfma_f32_16x16x32_bf16 v[146:149], v[54:57], v[218:221], v[18:21]
	v_mfma_f32_16x16x32_bf16 v[18:21], v[58:61], v[214:217], v[42:45]
	v_mfma_f32_16x16x32_bf16 v[194:197], v[54:57], v[142:145], v[66:69]
	v_mfma_f32_16x16x32_bf16 v[142:145], v[62:65], v[218:221], v[18:21]
	s_mov_b32 m0, s44
	v_lshl_add_u64 v[70:71], v[242:243], 0, s[20:21]
	s_barrier
	s_nop 1
	ds_read_b128 v[18:21], v222 offset:49152
	ds_read_b128 v[22:25], v222 offset:50176
	ds_read_b128 v[26:29], v222 offset:51200
	ds_read_b128 v[30:33], v222 offset:52224
	ds_read_b128 v[34:37], v222 offset:53248
	ds_read_b128 v[38:41], v222 offset:54272
	ds_read_b128 v[42:45], v222 offset:55296
	ds_read_b128 v[66:69], v222 offset:56320
	global_load_lds_dwordx4 v[70:71], off
	s_mov_b32 m0, s45
	v_lshl_add_u64 v[70:71], v[224:225], 0, s[20:21]
	global_load_lds_dwordx4 v[70:71], off
	s_barrier
	s_waitcnt lgkmcnt(0)
	v_mfma_f32_16x16x32_bf16 v[70:73], v[86:89], v[18:21], v[138:141]
	v_mfma_f32_16x16x32_bf16 v[138:141], v[90:93], v[22:25], v[70:73]
	v_mfma_f32_16x16x32_bf16 v[70:73], v[114:117], v[18:21], v[134:137]
	v_mfma_f32_16x16x32_bf16 v[134:137], v[126:129], v[22:25], v[70:73]
	v_mfma_f32_16x16x32_bf16 v[70:73], v[86:89], v[26:29], v[122:125]
	v_mfma_f32_16x16x32_bf16 v[122:125], v[90:93], v[30:33], v[70:73]
	v_mfma_f32_16x16x32_bf16 v[70:73], v[114:117], v[26:29], v[118:121]
	v_mfma_f32_16x16x32_bf16 v[118:121], v[126:129], v[30:33], v[70:73]
	v_mfma_f32_16x16x32_bf16 v[70:73], v[86:89], v[34:37], v[106:109]
	v_mfma_f32_16x16x32_bf16 v[2:5], v[86:89], v[42:45], v[2:5]
	v_mfma_f32_16x16x32_bf16 v[106:109], v[90:93], v[38:41], v[70:73]
	v_mfma_f32_16x16x32_bf16 v[70:73], v[114:117], v[34:37], v[102:105]
	v_mfma_f32_16x16x32_bf16 v[90:93], v[90:93], v[66:69], v[2:5]
	v_mfma_f32_16x16x32_bf16 v[2:5], v[114:117], v[42:45], v[6:9]
	v_mfma_f32_16x16x32_bf16 v[102:105], v[126:129], v[38:41], v[70:73]
	v_mfma_f32_16x16x32_bf16 v[86:89], v[126:129], v[66:69], v[2:5]
	s_barrier
	s_add_u32 s8, s8, 0x40080
	s_addc_u32 s9, s9, 0
	s_add_i32 s26, s26, s37
	s_nop 0
	s_mov_b32 m0, s26
	v_lshl_add_u64 v[2:3], s[8:9], 0, v[230:231]
	global_load_lds_dwordx4 v[2:3], off
	s_add_i32 m0, s26, 0x2000
	v_lshl_add_u64 v[2:3], s[8:9], 0, v[226:227]
	global_load_lds_dwordx4 v[2:3], off
	s_waitcnt vmcnt(6)
	s_barrier
	v_mfma_f32_16x16x32_bf16 v[2:5], v[50:53], v[18:21], v[10:13]
	v_mfma_f32_16x16x32_bf16 v[130:133], v[54:57], v[22:25], v[2:5]
	v_mfma_f32_16x16x32_bf16 v[2:5], v[58:61], v[18:21], v[14:17]
	v_mfma_f32_16x16x32_bf16 v[126:129], v[62:65], v[22:25], v[2:5]
	v_mfma_f32_16x16x32_bf16 v[2:5], v[50:53], v[26:29], v[46:49]
	v_mfma_f32_16x16x32_bf16 v[114:117], v[54:57], v[30:33], v[2:5]
	v_mfma_f32_16x16x32_bf16 v[2:5], v[58:61], v[26:29], v[110:113]
	v_mfma_f32_16x16x32_bf16 v[110:113], v[62:65], v[30:33], v[2:5]
	v_mfma_f32_16x16x32_bf16 v[2:5], v[50:53], v[34:37], v[98:101]
	v_mfma_f32_16x16x32_bf16 v[98:101], v[54:57], v[38:41], v[2:5]
	v_mfma_f32_16x16x32_bf16 v[2:5], v[58:61], v[34:37], v[94:97]
	v_mfma_f32_16x16x32_bf16 v[94:97], v[62:65], v[38:41], v[2:5]
	v_mfma_f32_16x16x32_bf16 v[2:5], v[50:53], v[42:45], v[82:85]
	v_mfma_f32_16x16x32_bf16 v[82:85], v[54:57], v[66:69], v[2:5]
	v_mfma_f32_16x16x32_bf16 v[2:5], v[58:61], v[42:45], v[78:81]
	v_mfma_f32_16x16x32_bf16 v[78:81], v[62:65], v[66:69], v[2:5]
	s_add_i32 s58, s58, 2
	s_add_u32 s6, s6, 0x100
	s_addc_u32 s7, s7, 0
	s_add_u32 s56, s56, 0x100
	s_addc_u32 s57, s57, 0
	s_cmp_gt_u32 s58, 13
	s_barrier
	s_cbranch_scc0 .LBB0_1152
